# de-serialised loads: dt tasks (16 A loads), ctx rows split-K partials (16), m4 retention gains (8), m4 ssd counted waits; GEMM setprio/wait trim
# speedup vs baseline: 1.0147x; 1.0029x over previous
; #define ROWS_UNPK(w, lo, hi) do { lo = (f32x4){bflo((w)[0]), bfhi((w)[0]), bflo((w)[1]), bfhi((w)[1])}; hi = (f32x4){bflo((w)[2]), bfhi((w)[2]), bflo((w)[3]), bfhi((w)[3])}; } while (0)
; template <bool XINB, bool XOUTB> __device__ __forceinline__ void ph_rows(Frame& F, int nrows, const void* xin_l, const void* xin_c, void* xout_l, void* xout_c, const bf16* Y, const bf16* Ypart, ...
;     ...
;         if (Y) {
;             f32x4 y[8]; float ss = 0.f;
;             if (!lat && Ypart) {
; #pragma unroll
;                 for (int jj = 0; jj < 4; ++jj) { f32x4 a0 = {0.f, 0.f, 0.f, 0.f}, a1 = a0;
; #pragma unroll
;                     for (int sp = 0; sp < KSPLIT; ++sp) { const v4u yw = *(const v4u*)(Ypart + ((size_t)sp * MC + (row - ML)) * D + ROWS_COL(jj)); f32x4 p0, p1; ROWS_UNPK(yw, p0, p1); a0 += p0; a1 += p1; }
;                     y[2 * jj] = a0; y[2 * jj + 1] = a1; }
;             } else {
; #pragma unroll
;                 for (int jj = 0; jj < 4; ++jj) ROWS_UNPK(yb_c[jj], y[2 * jj], y[2 * jj + 1]);
.LBB0_578:
	s_andn2_b64 vcc, exec, s[18:19]
	s_cbranch_vccnz .LBB0_580
	s_add_i32 s92, s31, 0xffffc000
	s_lshl_b64 s[18:19], s[92:93], 12
	v_lshl_add_u64 v[66:67], v[94:95], 0, s[18:19]
	s_mov_b32 s18, 0x400000
	v_add_co_u32_e32 v64, vcc, s18, v66
	s_nop 1
	v_addc_co_u32_e32 v65, vcc, 0, v67, vcc
	s_mov_b32 s18, 0x800000
	v_add_co_u32_e32 v62, vcc, s18, v66
	s_nop 1
	v_addc_co_u32_e32 v63, vcc, 0, v67, vcc
	s_mov_b32 s18, 0xc00000
	v_add_co_u32_e32 v60, vcc, s18, v66
	s_nop 1
	v_addc_co_u32_e32 v61, vcc, 0, v67, vcc
	global_load_dwordx4 v[144:147], v[66:67], off
	global_load_dwordx4 v[148:151], v[64:65], off
	global_load_dwordx4 v[152:155], v[62:63], off
	global_load_dwordx4 v[156:159], v[60:61], off
	global_load_dwordx4 v[160:163], v[66:67], off offset:1024
	global_load_dwordx4 v[164:167], v[64:65], off offset:1024
	global_load_dwordx4 v[172:175], v[62:63], off offset:1024
	global_load_dwordx4 v[176:179], v[60:61], off offset:1024
	global_load_dwordx4 v[180:183], v[66:67], off offset:2048
	global_load_dwordx4 v[184:187], v[64:65], off offset:2048
	global_load_dwordx4 v[188:191], v[62:63], off offset:2048
	global_load_dwordx4 v[192:195], v[60:61], off offset:2048
	global_load_dwordx4 v[196:199], v[66:67], off offset:3072
	global_load_dwordx4 v[200:203], v[64:65], off offset:3072
	global_load_dwordx4 v[204:207], v[62:63], off offset:3072
	global_load_dwordx4 v[208:211], v[60:61], off offset:3072
	s_waitcnt vmcnt(15)
	v_mov_b32_e32 v36, v144
	v_mov_b32_e32 v37, v145
	v_mov_b32_e32 v38, v146
	v_mov_b32_e32 v39, v147
	v_lshlrev_b32_e32 v40, 16, v36
	v_and_b32_e32 v41, 0xffff0000, v36
	v_lshlrev_b32_e32 v36, 16, v37
	v_and_b32_e32 v37, 0xffff0000, v37
	v_lshlrev_b32_e32 v42, 16, v38
	v_and_b32_e32 v43, 0xffff0000, v38
	v_lshlrev_b32_e32 v38, 16, v39
	v_and_b32_e32 v39, 0xffff0000, v39
	v_pk_add_f32 v[44:45], v[36:37], 0 op_sel_hi:[1,0]
	v_pk_add_f32 v[46:47], v[38:39], 0 op_sel_hi:[1,0]
	v_pk_add_f32 v[40:41], v[40:41], 0 op_sel_hi:[1,0]
	v_pk_add_f32 v[42:43], v[42:43], 0 op_sel_hi:[1,0]
	s_waitcnt vmcnt(14)
	v_mov_b32_e32 v36, v148
	v_mov_b32_e32 v37, v149
	v_mov_b32_e32 v38, v150
	v_mov_b32_e32 v39, v151
	v_lshlrev_b32_e32 v48, 16, v36
	v_and_b32_e32 v49, 0xffff0000, v36
	v_lshlrev_b32_e32 v36, 16, v37
	v_and_b32_e32 v37, 0xffff0000, v37
	v_lshlrev_b32_e32 v50, 16, v38
	v_and_b32_e32 v51, 0xffff0000, v38
	v_lshlrev_b32_e32 v38, 16, v39
	v_and_b32_e32 v39, 0xffff0000, v39
	v_pk_add_f32 v[44:45], v[44:45], v[36:37]
	v_pk_add_f32 v[46:47], v[46:47], v[38:39]
	v_pk_add_f32 v[40:41], v[40:41], v[48:49]
	v_pk_add_f32 v[42:43], v[42:43], v[50:51]
	s_waitcnt vmcnt(13)
	v_mov_b32_e32 v36, v152
	v_mov_b32_e32 v37, v153
	v_mov_b32_e32 v38, v154
	v_mov_b32_e32 v39, v155
	v_lshlrev_b32_e32 v48, 16, v36
	v_and_b32_e32 v49, 0xffff0000, v36
	v_lshlrev_b32_e32 v36, 16, v37
	v_and_b32_e32 v37, 0xffff0000, v37
	v_lshlrev_b32_e32 v50, 16, v38
	v_and_b32_e32 v51, 0xffff0000, v38
	v_lshlrev_b32_e32 v38, 16, v39
	v_and_b32_e32 v39, 0xffff0000, v39
	v_pk_add_f32 v[40:41], v[40:41], v[48:49]
	v_pk_add_f32 v[44:45], v[44:45], v[36:37]
	v_pk_add_f32 v[48:49], v[42:43], v[50:51]
	v_pk_add_f32 v[42:43], v[46:47], v[38:39]
	s_waitcnt vmcnt(12)
	v_mov_b32_e32 v36, v156
	v_mov_b32_e32 v37, v157
	v_mov_b32_e32 v38, v158
	v_mov_b32_e32 v39, v159
	v_lshlrev_b32_e32 v46, 16, v36
	v_and_b32_e32 v47, 0xffff0000, v36
	v_lshlrev_b32_e32 v36, 16, v37
	v_and_b32_e32 v37, 0xffff0000, v37
	v_lshlrev_b32_e32 v50, 16, v38
	v_and_b32_e32 v51, 0xffff0000, v38
	v_lshlrev_b32_e32 v52, 16, v39
	v_and_b32_e32 v53, 0xffff0000, v39
	v_pk_add_f32 v[38:39], v[44:45], v[36:37]
	v_pk_add_f32 v[36:37], v[40:41], v[46:47]
	v_pk_add_f32 v[40:41], v[48:49], v[50:51]
	v_pk_add_f32 v[42:43], v[42:43], v[52:53]
	s_waitcnt vmcnt(11)
	v_mov_b32_e32 v44, v160
	v_mov_b32_e32 v45, v161
	v_mov_b32_e32 v46, v162
	v_mov_b32_e32 v47, v163
	v_lshlrev_b32_e32 v48, 16, v44
	v_and_b32_e32 v49, 0xffff0000, v44
	v_lshlrev_b32_e32 v44, 16, v45
	v_and_b32_e32 v45, 0xffff0000, v45
	v_lshlrev_b32_e32 v50, 16, v46
	v_and_b32_e32 v51, 0xffff0000, v46
	v_lshlrev_b32_e32 v46, 16, v47
	v_and_b32_e32 v47, 0xffff0000, v47
	v_pk_add_f32 v[52:53], v[44:45], 0 op_sel_hi:[1,0]
	v_pk_add_f32 v[54:55], v[46:47], 0 op_sel_hi:[1,0]
	v_pk_add_f32 v[48:49], v[48:49], 0 op_sel_hi:[1,0]
	v_pk_add_f32 v[50:51], v[50:51], 0 op_sel_hi:[1,0]
	s_waitcnt vmcnt(10)
	v_mov_b32_e32 v44, v164
	v_mov_b32_e32 v45, v165
	v_mov_b32_e32 v46, v166
	v_mov_b32_e32 v47, v167
	v_lshlrev_b32_e32 v56, 16, v44
	v_and_b32_e32 v57, 0xffff0000, v44
	v_lshlrev_b32_e32 v44, 16, v45
	v_and_b32_e32 v45, 0xffff0000, v45
	v_lshlrev_b32_e32 v58, 16, v46
	v_and_b32_e32 v59, 0xffff0000, v46
	v_lshlrev_b32_e32 v46, 16, v47
	v_and_b32_e32 v47, 0xffff0000, v47
	v_pk_add_f32 v[52:53], v[52:53], v[44:45]
	v_pk_add_f32 v[54:55], v[54:55], v[46:47]
	v_pk_add_f32 v[48:49], v[48:49], v[56:57]
	v_pk_add_f32 v[50:51], v[50:51], v[58:59]
	s_waitcnt vmcnt(9)
	v_mov_b32_e32 v44, v172
	v_mov_b32_e32 v45, v173
	v_mov_b32_e32 v46, v174
	v_mov_b32_e32 v47, v175
	v_lshlrev_b32_e32 v56, 16, v44
	v_and_b32_e32 v57, 0xffff0000, v44
	v_lshlrev_b32_e32 v44, 16, v45
	v_and_b32_e32 v45, 0xffff0000, v45
	v_lshlrev_b32_e32 v58, 16, v46
	v_and_b32_e32 v59, 0xffff0000, v46
	v_lshlrev_b32_e32 v46, 16, v47
	v_and_b32_e32 v47, 0xffff0000, v47
	v_pk_add_f32 v[48:49], v[48:49], v[56:57]
	v_pk_add_f32 v[52:53], v[52:53], v[44:45]
	v_pk_add_f32 v[56:57], v[50:51], v[58:59]
	v_pk_add_f32 v[50:51], v[54:55], v[46:47]
	s_waitcnt vmcnt(8)
; #define ROWS_UNPK(w, lo, hi) do { lo = (f32x4){bflo((w)[0]), bfhi((w)[0]), bflo((w)[1]), bfhi((w)[1])}; hi = (f32x4){bflo((w)[2]), bfhi((w)[2]), bflo((w)[3]), bfhi((w)[3])}; } while (0)
; template <bool XINB, bool XOUTB> __device__ __forceinline__ void ph_rows(Frame& F, int nrows, const void* xin_l, const void* xin_c, void* xout_l, void* xout_c, const bf16* Y, const bf16* Ypart, ...
;     ...
;             if (!lat && Ypart) {
; #pragma unroll
;                 for (int jj = 0; jj < 4; ++jj) { f32x4 a0 = {0.f, 0.f, 0.f, 0.f}, a1 = a0;
; #pragma unroll
;                     for (int sp = 0; sp < KSPLIT; ++sp) { const v4u yw = *(const v4u*)(Ypart + ((size_t)sp * MC + (row - ML)) * D + ROWS_COL(jj)); f32x4 p0, p1; ROWS_UNPK(yw, p0, p1); a0 += p0; a1 += p1; }
;                     y[2 * jj] = a0; y[2 * jj + 1] = a1; }
	v_mov_b32_e32 v44, v176
	v_mov_b32_e32 v45, v177
	v_mov_b32_e32 v46, v178
	v_mov_b32_e32 v47, v179
	v_lshlrev_b32_e32 v54, 16, v44
	v_and_b32_e32 v55, 0xffff0000, v44
	v_lshlrev_b32_e32 v44, 16, v45
	v_and_b32_e32 v45, 0xffff0000, v45
	v_lshlrev_b32_e32 v58, 16, v46
	v_and_b32_e32 v59, 0xffff0000, v46
	v_lshlrev_b32_e32 v68, 16, v47
	v_and_b32_e32 v69, 0xffff0000, v47
	v_pk_add_f32 v[46:47], v[52:53], v[44:45]
	v_pk_add_f32 v[44:45], v[48:49], v[54:55]
	v_pk_add_f32 v[48:49], v[56:57], v[58:59]
	v_pk_add_f32 v[50:51], v[50:51], v[68:69]
	s_waitcnt vmcnt(7)
	v_mov_b32_e32 v52, v180
	v_mov_b32_e32 v53, v181
	v_mov_b32_e32 v54, v182
	v_mov_b32_e32 v55, v183
	v_lshlrev_b32_e32 v56, 16, v52
	v_and_b32_e32 v57, 0xffff0000, v52
	v_lshlrev_b32_e32 v52, 16, v53
	v_and_b32_e32 v53, 0xffff0000, v53
	v_lshlrev_b32_e32 v58, 16, v54
	v_and_b32_e32 v59, 0xffff0000, v54
	v_lshlrev_b32_e32 v54, 16, v55
	v_and_b32_e32 v55, 0xffff0000, v55
	v_pk_add_f32 v[68:69], v[52:53], 0 op_sel_hi:[1,0]
	v_pk_add_f32 v[70:71], v[54:55], 0 op_sel_hi:[1,0]
	v_pk_add_f32 v[56:57], v[56:57], 0 op_sel_hi:[1,0]
	v_pk_add_f32 v[58:59], v[58:59], 0 op_sel_hi:[1,0]
	s_waitcnt vmcnt(6)
	v_mov_b32_e32 v52, v184
	v_mov_b32_e32 v53, v185
	v_mov_b32_e32 v54, v186
	v_mov_b32_e32 v55, v187
	v_lshlrev_b32_e32 v72, 16, v52
	v_and_b32_e32 v73, 0xffff0000, v52
	v_lshlrev_b32_e32 v52, 16, v53
	v_and_b32_e32 v53, 0xffff0000, v53
	v_lshlrev_b32_e32 v74, 16, v54
	v_and_b32_e32 v75, 0xffff0000, v54
	v_lshlrev_b32_e32 v54, 16, v55
	v_and_b32_e32 v55, 0xffff0000, v55
	v_pk_add_f32 v[68:69], v[68:69], v[52:53]
	v_pk_add_f32 v[70:71], v[70:71], v[54:55]
	v_pk_add_f32 v[56:57], v[56:57], v[72:73]
	v_pk_add_f32 v[58:59], v[58:59], v[74:75]
	s_waitcnt vmcnt(5)
	v_mov_b32_e32 v52, v188
	v_mov_b32_e32 v53, v189
	v_mov_b32_e32 v54, v190
	v_mov_b32_e32 v55, v191
	v_lshlrev_b32_e32 v72, 16, v52
	v_and_b32_e32 v73, 0xffff0000, v52
	v_lshlrev_b32_e32 v52, 16, v53
	v_and_b32_e32 v53, 0xffff0000, v53
	v_lshlrev_b32_e32 v74, 16, v54
	v_and_b32_e32 v75, 0xffff0000, v54
	v_lshlrev_b32_e32 v54, 16, v55
	v_and_b32_e32 v55, 0xffff0000, v55
	v_pk_add_f32 v[56:57], v[56:57], v[72:73]
	v_pk_add_f32 v[68:69], v[68:69], v[52:53]
	v_pk_add_f32 v[72:73], v[58:59], v[74:75]
	v_pk_add_f32 v[58:59], v[70:71], v[54:55]
	s_waitcnt vmcnt(4)
	v_mov_b32_e32 v52, v192
	v_mov_b32_e32 v53, v193
	v_mov_b32_e32 v54, v194
	v_mov_b32_e32 v55, v195
	v_lshlrev_b32_e32 v70, 16, v52
	v_and_b32_e32 v71, 0xffff0000, v52
	v_lshlrev_b32_e32 v52, 16, v53
	v_and_b32_e32 v53, 0xffff0000, v53
	v_lshlrev_b32_e32 v74, 16, v54
	v_and_b32_e32 v75, 0xffff0000, v54
	v_lshlrev_b32_e32 v76, 16, v55
	v_and_b32_e32 v77, 0xffff0000, v55
	v_pk_add_f32 v[54:55], v[68:69], v[52:53]
	v_pk_add_f32 v[52:53], v[56:57], v[70:71]
	v_pk_add_f32 v[56:57], v[72:73], v[74:75]
	v_pk_add_f32 v[58:59], v[58:59], v[76:77]
	s_waitcnt vmcnt(3)
	v_mov_b32_e32 v66, v196
	v_mov_b32_e32 v67, v197
	v_mov_b32_e32 v68, v198
	v_mov_b32_e32 v69, v199
	v_lshlrev_b32_e32 v70, 16, v66
	v_and_b32_e32 v71, 0xffff0000, v66
	v_lshlrev_b32_e32 v66, 16, v67
	v_and_b32_e32 v67, 0xffff0000, v67
	v_pk_add_f32 v[74:75], v[66:67], 0 op_sel_hi:[1,0]
	v_lshlrev_b32_e32 v72, 16, v68
	v_and_b32_e32 v73, 0xffff0000, v68
	v_lshlrev_b32_e32 v68, 16, v69
	v_and_b32_e32 v69, 0xffff0000, v69
	v_pk_add_f32 v[70:71], v[70:71], 0 op_sel_hi:[1,0]
	v_pk_add_f32 v[68:69], v[68:69], 0 op_sel_hi:[1,0]
	v_pk_add_f32 v[72:73], v[72:73], 0 op_sel_hi:[1,0]
	s_waitcnt vmcnt(2)
	v_mov_b32_e32 v64, v200
	v_mov_b32_e32 v65, v201
	v_mov_b32_e32 v66, v202
	v_mov_b32_e32 v67, v203
	v_lshlrev_b32_e32 v76, 16, v64
	v_and_b32_e32 v77, 0xffff0000, v64
	v_lshlrev_b32_e32 v64, 16, v65
	v_and_b32_e32 v65, 0xffff0000, v65
	v_pk_add_f32 v[74:75], v[74:75], v[64:65]
	v_lshlrev_b32_e32 v78, 16, v66
	v_and_b32_e32 v79, 0xffff0000, v66
	v_lshlrev_b32_e32 v66, 16, v67
	v_and_b32_e32 v67, 0xffff0000, v67
	v_pk_add_f32 v[70:71], v[70:71], v[76:77]
	v_pk_add_f32 v[66:67], v[68:69], v[66:67]
	v_pk_add_f32 v[72:73], v[72:73], v[78:79]
	s_waitcnt vmcnt(1)
	v_mov_b32_e32 v62, v204
	v_mov_b32_e32 v63, v205
	v_mov_b32_e32 v64, v206
	v_mov_b32_e32 v65, v207
	v_lshlrev_b32_e32 v68, 16, v62
	v_and_b32_e32 v69, 0xffff0000, v62
	v_lshlrev_b32_e32 v62, 16, v63
	v_and_b32_e32 v63, 0xffff0000, v63
	v_pk_add_f32 v[68:69], v[70:71], v[68:69]
	v_pk_add_f32 v[70:71], v[74:75], v[62:63]
	v_lshlrev_b32_e32 v76, 16, v64
	v_and_b32_e32 v77, 0xffff0000, v64
	v_lshlrev_b32_e32 v78, 16, v65
	v_and_b32_e32 v79, 0xffff0000, v65
	v_pk_add_f32 v[64:65], v[72:73], v[76:77]
	v_pk_add_f32 v[66:67], v[66:67], v[78:79]
	s_waitcnt vmcnt(0)
	v_mov_b32_e32 v60, v208
	v_mov_b32_e32 v61, v209
	v_mov_b32_e32 v62, v210
	v_mov_b32_e32 v63, v211
	v_lshlrev_b32_e32 v72, 16, v60
	v_and_b32_e32 v73, 0xffff0000, v60
	v_lshlrev_b32_e32 v60, 16, v61
	v_and_b32_e32 v61, 0xffff0000, v61
	v_lshlrev_b32_e32 v74, 16, v62
	v_and_b32_e32 v75, 0xffff0000, v62
	v_lshlrev_b32_e32 v76, 16, v63
	v_and_b32_e32 v77, 0xffff0000, v63
	v_pk_add_f32 v[62:63], v[70:71], v[60:61]
	v_pk_add_f32 v[60:61], v[68:69], v[72:73]
	v_pk_add_f32 v[66:67], v[66:67], v[76:77]
	v_pk_add_f32 v[64:65], v[64:65], v[74:75]

; #define ROWS_UNPK(w, lo, hi) do { lo = (f32x4){bflo((w)[0]), bfhi((w)[0]), bflo((w)[1]), bfhi((w)[1])}; hi = (f32x4){bflo((w)[2]), bfhi((w)[2]), bflo((w)[3]), bfhi((w)[3])}; } while (0)
; template <bool XINB, bool XOUTB> __device__ __forceinline__ void ph_rows(Frame& F, int nrows, const void* xin_l, const void* xin_c, void* xout_l, void* xout_c, const bf16* Y, const bf16* Ypart, ...
;     ...
;             if (!lat && Ypart) {
; #pragma unroll
;                 for (int jj = 0; jj < 4; ++jj) { f32x4 a0 = {0.f, 0.f, 0.f, 0.f}, a1 = a0;
; #pragma unroll
;                     for (int sp = 0; sp < KSPLIT; ++sp) { const v4u yw = *(const v4u*)(Ypart + ((size_t)sp * MC + (row - ML)) * D + ROWS_COL(jj)); f32x4 p0, p1; ROWS_UNPK(yw, p0, p1); a0 += p0; a1 += p1; }
;                     y[2 * jj] = a0; y[2 * jj + 1] = a1; }
.LBB0_598:
	s_andn2_b64 vcc, exec, s[20:21]
	s_mov_b64 s[20:21], 0
	s_cbranch_vccnz .LBB0_590
	s_add_i32 s92, s22, 0xffffc000
	s_lshl_b64 s[20:21], s[92:93], 12
	v_lshl_add_u64 v[114:115], v[134:135], 0, s[20:21]
	s_mov_b32 s20, 0x400000
	v_add_co_u32_e32 v112, vcc, s20, v114
	s_nop 1
	v_addc_co_u32_e32 v113, vcc, 0, v115, vcc
	s_mov_b32 s20, 0x800000
	v_add_co_u32_e32 v110, vcc, s20, v114
	s_nop 1
	v_addc_co_u32_e32 v111, vcc, 0, v115, vcc
	s_mov_b32 s20, 0xc00000
	v_add_co_u32_e32 v108, vcc, s20, v114
	s_nop 1
	v_addc_co_u32_e32 v109, vcc, 0, v115, vcc
	global_load_dwordx4 v[144:147], v[114:115], off
	global_load_dwordx4 v[148:151], v[112:113], off
	global_load_dwordx4 v[152:155], v[110:111], off
	global_load_dwordx4 v[156:159], v[108:109], off
	global_load_dwordx4 v[160:163], v[114:115], off offset:1024
	global_load_dwordx4 v[164:167], v[112:113], off offset:1024
	global_load_dwordx4 v[172:175], v[110:111], off offset:1024
	global_load_dwordx4 v[176:179], v[108:109], off offset:1024
	global_load_dwordx4 v[180:183], v[114:115], off offset:2048
	global_load_dwordx4 v[184:187], v[112:113], off offset:2048
	global_load_dwordx4 v[188:191], v[110:111], off offset:2048
	global_load_dwordx4 v[192:195], v[108:109], off offset:2048
	global_load_dwordx4 v[196:199], v[114:115], off offset:3072
	global_load_dwordx4 v[200:203], v[112:113], off offset:3072
	global_load_dwordx4 v[204:207], v[110:111], off offset:3072
	global_load_dwordx4 v[208:211], v[108:109], off offset:3072
	s_mov_b64 s[20:21], 0x4000000
	s_waitcnt vmcnt(15)
	v_mov_b32_e32 v84, v144
	v_mov_b32_e32 v85, v145
	v_mov_b32_e32 v86, v146
	v_mov_b32_e32 v87, v147
	v_lshlrev_b32_e32 v88, 16, v84
	v_and_b32_e32 v89, 0xffff0000, v84
	v_lshlrev_b32_e32 v84, 16, v85
	v_and_b32_e32 v85, 0xffff0000, v85
	v_lshlrev_b32_e32 v90, 16, v86
	v_and_b32_e32 v91, 0xffff0000, v86
	v_lshlrev_b32_e32 v86, 16, v87
	v_and_b32_e32 v87, 0xffff0000, v87
	v_pk_add_f32 v[92:93], v[84:85], 0 op_sel_hi:[1,0]
	v_pk_add_f32 v[94:95], v[86:87], 0 op_sel_hi:[1,0]
	v_pk_add_f32 v[88:89], v[88:89], 0 op_sel_hi:[1,0]
	v_pk_add_f32 v[90:91], v[90:91], 0 op_sel_hi:[1,0]
	s_waitcnt vmcnt(14)
	v_mov_b32_e32 v84, v148
	v_mov_b32_e32 v85, v149
	v_mov_b32_e32 v86, v150
	v_mov_b32_e32 v87, v151
	v_lshlrev_b32_e32 v96, 16, v84
	v_and_b32_e32 v97, 0xffff0000, v84
	v_lshlrev_b32_e32 v84, 16, v85
	v_and_b32_e32 v85, 0xffff0000, v85
	v_lshlrev_b32_e32 v98, 16, v86
	v_and_b32_e32 v99, 0xffff0000, v86
	v_lshlrev_b32_e32 v86, 16, v87
	v_and_b32_e32 v87, 0xffff0000, v87
	v_pk_add_f32 v[92:93], v[92:93], v[84:85]
	v_pk_add_f32 v[94:95], v[94:95], v[86:87]
	v_pk_add_f32 v[88:89], v[88:89], v[96:97]
	v_pk_add_f32 v[90:91], v[90:91], v[98:99]
	s_waitcnt vmcnt(13)
	v_mov_b32_e32 v84, v152
	v_mov_b32_e32 v85, v153
	v_mov_b32_e32 v86, v154
	v_mov_b32_e32 v87, v155
	v_lshlrev_b32_e32 v96, 16, v84
	v_and_b32_e32 v97, 0xffff0000, v84
	v_lshlrev_b32_e32 v84, 16, v85
	v_and_b32_e32 v85, 0xffff0000, v85
	v_lshlrev_b32_e32 v98, 16, v86
	v_and_b32_e32 v99, 0xffff0000, v86
	v_lshlrev_b32_e32 v86, 16, v87
	v_and_b32_e32 v87, 0xffff0000, v87
	v_pk_add_f32 v[88:89], v[88:89], v[96:97]
	v_pk_add_f32 v[92:93], v[92:93], v[84:85]
	v_pk_add_f32 v[96:97], v[90:91], v[98:99]
	v_pk_add_f32 v[90:91], v[94:95], v[86:87]
	s_waitcnt vmcnt(12)
	v_mov_b32_e32 v84, v156
	v_mov_b32_e32 v85, v157
	v_mov_b32_e32 v86, v158
	v_mov_b32_e32 v87, v159
	v_lshlrev_b32_e32 v94, 16, v84
	v_and_b32_e32 v95, 0xffff0000, v84
	v_lshlrev_b32_e32 v84, 16, v85
	v_and_b32_e32 v85, 0xffff0000, v85
	v_lshlrev_b32_e32 v98, 16, v86
	v_and_b32_e32 v99, 0xffff0000, v86
	v_lshlrev_b32_e32 v100, 16, v87
	v_and_b32_e32 v101, 0xffff0000, v87
	v_pk_add_f32 v[86:87], v[92:93], v[84:85]
	v_pk_add_f32 v[84:85], v[88:89], v[94:95]
	v_pk_add_f32 v[88:89], v[96:97], v[98:99]
	v_pk_add_f32 v[90:91], v[90:91], v[100:101]
	s_waitcnt vmcnt(11)
	v_mov_b32_e32 v92, v160
	v_mov_b32_e32 v93, v161
	v_mov_b32_e32 v94, v162
	v_mov_b32_e32 v95, v163
	v_lshlrev_b32_e32 v96, 16, v92
	v_and_b32_e32 v97, 0xffff0000, v92
	v_lshlrev_b32_e32 v92, 16, v93
	v_and_b32_e32 v93, 0xffff0000, v93
	v_lshlrev_b32_e32 v98, 16, v94
	v_and_b32_e32 v99, 0xffff0000, v94
	v_lshlrev_b32_e32 v94, 16, v95
	v_and_b32_e32 v95, 0xffff0000, v95
	v_pk_add_f32 v[100:101], v[92:93], 0 op_sel_hi:[1,0]
	v_pk_add_f32 v[102:103], v[94:95], 0 op_sel_hi:[1,0]
	v_pk_add_f32 v[96:97], v[96:97], 0 op_sel_hi:[1,0]
	v_pk_add_f32 v[98:99], v[98:99], 0 op_sel_hi:[1,0]
	s_waitcnt vmcnt(10)
	v_mov_b32_e32 v92, v164
	v_mov_b32_e32 v93, v165
	v_mov_b32_e32 v94, v166
	v_mov_b32_e32 v95, v167
	v_lshlrev_b32_e32 v104, 16, v92
	v_and_b32_e32 v105, 0xffff0000, v92
	v_lshlrev_b32_e32 v92, 16, v93
	v_and_b32_e32 v93, 0xffff0000, v93
	v_lshlrev_b32_e32 v106, 16, v94
	v_and_b32_e32 v107, 0xffff0000, v94
	v_lshlrev_b32_e32 v94, 16, v95
	v_and_b32_e32 v95, 0xffff0000, v95
	v_pk_add_f32 v[100:101], v[100:101], v[92:93]
	v_pk_add_f32 v[102:103], v[102:103], v[94:95]
	v_pk_add_f32 v[96:97], v[96:97], v[104:105]
	v_pk_add_f32 v[98:99], v[98:99], v[106:107]
	s_waitcnt vmcnt(9)
	v_mov_b32_e32 v92, v172
	v_mov_b32_e32 v93, v173
	v_mov_b32_e32 v94, v174
	v_mov_b32_e32 v95, v175
	v_lshlrev_b32_e32 v104, 16, v92
	v_and_b32_e32 v105, 0xffff0000, v92
	v_lshlrev_b32_e32 v92, 16, v93
	v_and_b32_e32 v93, 0xffff0000, v93
	v_lshlrev_b32_e32 v106, 16, v94
	v_and_b32_e32 v107, 0xffff0000, v94
	v_lshlrev_b32_e32 v94, 16, v95
	v_and_b32_e32 v95, 0xffff0000, v95
	v_pk_add_f32 v[96:97], v[96:97], v[104:105]
	v_pk_add_f32 v[100:101], v[100:101], v[92:93]
	v_pk_add_f32 v[104:105], v[98:99], v[106:107]
	v_pk_add_f32 v[98:99], v[102:103], v[94:95]
	s_waitcnt vmcnt(8)
; #define ROWS_UNPK(w, lo, hi) do { lo = (f32x4){bflo((w)[0]), bfhi((w)[0]), bflo((w)[1]), bfhi((w)[1])}; hi = (f32x4){bflo((w)[2]), bfhi((w)[2]), bflo((w)[3]), bfhi((w)[3])}; } while (0)
; template <bool XINB, bool XOUTB> __device__ __forceinline__ void ph_rows(Frame& F, int nrows, const void* xin_l, const void* xin_c, void* xout_l, void* xout_c, const bf16* Y, const bf16* Ypart, ...
;     ...
;             if (!lat && Ypart) {
; #pragma unroll
;                 for (int jj = 0; jj < 4; ++jj) { f32x4 a0 = {0.f, 0.f, 0.f, 0.f}, a1 = a0;
; #pragma unroll
;                     for (int sp = 0; sp < KSPLIT; ++sp) { const v4u yw = *(const v4u*)(Ypart + ((size_t)sp * MC + (row - ML)) * D + ROWS_COL(jj)); f32x4 p0, p1; ROWS_UNPK(yw, p0, p1); a0 += p0; a1 += p1; }
;                     y[2 * jj] = a0; y[2 * jj + 1] = a1; }
	v_mov_b32_e32 v92, v176
	v_mov_b32_e32 v93, v177
	v_mov_b32_e32 v94, v178
	v_mov_b32_e32 v95, v179
	v_lshlrev_b32_e32 v102, 16, v92
	v_and_b32_e32 v103, 0xffff0000, v92
	v_lshlrev_b32_e32 v92, 16, v93
	v_and_b32_e32 v93, 0xffff0000, v93
	v_lshlrev_b32_e32 v106, 16, v94
	v_and_b32_e32 v107, 0xffff0000, v94
	v_lshlrev_b32_e32 v116, 16, v95
	v_and_b32_e32 v117, 0xffff0000, v95
	v_pk_add_f32 v[94:95], v[100:101], v[92:93]
	v_pk_add_f32 v[92:93], v[96:97], v[102:103]
	v_pk_add_f32 v[96:97], v[104:105], v[106:107]
	v_pk_add_f32 v[98:99], v[98:99], v[116:117]
	s_waitcnt vmcnt(7)
	v_mov_b32_e32 v100, v180
	v_mov_b32_e32 v101, v181
	v_mov_b32_e32 v102, v182
	v_mov_b32_e32 v103, v183
	v_lshlrev_b32_e32 v104, 16, v100
	v_and_b32_e32 v105, 0xffff0000, v100
	v_lshlrev_b32_e32 v100, 16, v101
	v_and_b32_e32 v101, 0xffff0000, v101
	v_lshlrev_b32_e32 v106, 16, v102
	v_and_b32_e32 v107, 0xffff0000, v102
	v_lshlrev_b32_e32 v102, 16, v103
	v_and_b32_e32 v103, 0xffff0000, v103
	v_pk_add_f32 v[116:117], v[100:101], 0 op_sel_hi:[1,0]
	v_pk_add_f32 v[118:119], v[102:103], 0 op_sel_hi:[1,0]
	v_pk_add_f32 v[104:105], v[104:105], 0 op_sel_hi:[1,0]
	v_pk_add_f32 v[106:107], v[106:107], 0 op_sel_hi:[1,0]
	s_waitcnt vmcnt(6)
	v_mov_b32_e32 v100, v184
	v_mov_b32_e32 v101, v185
	v_mov_b32_e32 v102, v186
	v_mov_b32_e32 v103, v187
	v_lshlrev_b32_e32 v120, 16, v100
	v_and_b32_e32 v121, 0xffff0000, v100
	v_lshlrev_b32_e32 v100, 16, v101
	v_and_b32_e32 v101, 0xffff0000, v101
	v_lshlrev_b32_e32 v122, 16, v102
	v_and_b32_e32 v123, 0xffff0000, v102
	v_lshlrev_b32_e32 v102, 16, v103
	v_and_b32_e32 v103, 0xffff0000, v103
	v_pk_add_f32 v[116:117], v[116:117], v[100:101]
	v_pk_add_f32 v[118:119], v[118:119], v[102:103]
	v_pk_add_f32 v[104:105], v[104:105], v[120:121]
	v_pk_add_f32 v[106:107], v[106:107], v[122:123]
	s_waitcnt vmcnt(5)
	v_mov_b32_e32 v100, v188
	v_mov_b32_e32 v101, v189
	v_mov_b32_e32 v102, v190
	v_mov_b32_e32 v103, v191
	v_lshlrev_b32_e32 v120, 16, v100
	v_and_b32_e32 v121, 0xffff0000, v100
	v_lshlrev_b32_e32 v100, 16, v101
	v_and_b32_e32 v101, 0xffff0000, v101
	v_lshlrev_b32_e32 v122, 16, v102
	v_and_b32_e32 v123, 0xffff0000, v102
	v_lshlrev_b32_e32 v102, 16, v103
	v_and_b32_e32 v103, 0xffff0000, v103
	v_pk_add_f32 v[104:105], v[104:105], v[120:121]
	v_pk_add_f32 v[116:117], v[116:117], v[100:101]
	v_pk_add_f32 v[120:121], v[106:107], v[122:123]
	v_pk_add_f32 v[106:107], v[118:119], v[102:103]
	s_waitcnt vmcnt(4)
	v_mov_b32_e32 v100, v192
	v_mov_b32_e32 v101, v193
	v_mov_b32_e32 v102, v194
	v_mov_b32_e32 v103, v195
	v_lshlrev_b32_e32 v118, 16, v100
	v_and_b32_e32 v119, 0xffff0000, v100
	v_lshlrev_b32_e32 v100, 16, v101
	v_and_b32_e32 v101, 0xffff0000, v101
	v_lshlrev_b32_e32 v122, 16, v102
	v_and_b32_e32 v123, 0xffff0000, v102
	v_lshlrev_b32_e32 v124, 16, v103
	v_and_b32_e32 v125, 0xffff0000, v103
	v_pk_add_f32 v[102:103], v[116:117], v[100:101]
	v_pk_add_f32 v[100:101], v[104:105], v[118:119]
	v_pk_add_f32 v[104:105], v[120:121], v[122:123]
	v_pk_add_f32 v[106:107], v[106:107], v[124:125]
	s_waitcnt vmcnt(3)
	v_mov_b32_e32 v114, v196
	v_mov_b32_e32 v115, v197
	v_mov_b32_e32 v116, v198
	v_mov_b32_e32 v117, v199
	v_lshlrev_b32_e32 v118, 16, v114
	v_and_b32_e32 v119, 0xffff0000, v114
	v_lshlrev_b32_e32 v114, 16, v115
	v_and_b32_e32 v115, 0xffff0000, v115
	v_pk_add_f32 v[122:123], v[114:115], 0 op_sel_hi:[1,0]
	v_lshlrev_b32_e32 v120, 16, v116
	v_and_b32_e32 v121, 0xffff0000, v116
	v_lshlrev_b32_e32 v116, 16, v117
	v_and_b32_e32 v117, 0xffff0000, v117
	v_pk_add_f32 v[118:119], v[118:119], 0 op_sel_hi:[1,0]
	v_pk_add_f32 v[116:117], v[116:117], 0 op_sel_hi:[1,0]
	v_pk_add_f32 v[120:121], v[120:121], 0 op_sel_hi:[1,0]
	s_waitcnt vmcnt(2)
	v_mov_b32_e32 v112, v200
	v_mov_b32_e32 v113, v201
	v_mov_b32_e32 v114, v202
	v_mov_b32_e32 v115, v203
	v_lshlrev_b32_e32 v124, 16, v112
	v_and_b32_e32 v125, 0xffff0000, v112
	v_lshlrev_b32_e32 v112, 16, v113
	v_and_b32_e32 v113, 0xffff0000, v113
	v_pk_add_f32 v[122:123], v[122:123], v[112:113]
	v_lshlrev_b32_e32 v126, 16, v114
	v_and_b32_e32 v127, 0xffff0000, v114
	v_lshlrev_b32_e32 v114, 16, v115
	v_and_b32_e32 v115, 0xffff0000, v115
	v_pk_add_f32 v[118:119], v[118:119], v[124:125]
	v_pk_add_f32 v[114:115], v[116:117], v[114:115]
	v_pk_add_f32 v[120:121], v[120:121], v[126:127]
	s_waitcnt vmcnt(1)
	v_mov_b32_e32 v110, v204
	v_mov_b32_e32 v111, v205
	v_mov_b32_e32 v112, v206
	v_mov_b32_e32 v113, v207
	v_lshlrev_b32_e32 v116, 16, v110
	v_and_b32_e32 v117, 0xffff0000, v110
	v_lshlrev_b32_e32 v110, 16, v111
	v_and_b32_e32 v111, 0xffff0000, v111
	v_pk_add_f32 v[116:117], v[118:119], v[116:117]
	v_pk_add_f32 v[118:119], v[122:123], v[110:111]
	v_lshlrev_b32_e32 v124, 16, v112
	v_and_b32_e32 v125, 0xffff0000, v112
	v_lshlrev_b32_e32 v126, 16, v113
	v_and_b32_e32 v127, 0xffff0000, v113
	v_pk_add_f32 v[112:113], v[120:121], v[124:125]
	v_pk_add_f32 v[114:115], v[114:115], v[126:127]
	s_waitcnt vmcnt(0)
	v_mov_b32_e32 v108, v208
	v_mov_b32_e32 v109, v209
	v_mov_b32_e32 v110, v210
	v_mov_b32_e32 v111, v211
	v_lshlrev_b32_e32 v120, 16, v108
	v_and_b32_e32 v121, 0xffff0000, v108
	v_lshlrev_b32_e32 v108, 16, v109
	v_and_b32_e32 v109, 0xffff0000, v109
	v_lshlrev_b32_e32 v122, 16, v110
	v_and_b32_e32 v123, 0xffff0000, v110
	v_lshlrev_b32_e32 v124, 16, v111
	v_and_b32_e32 v125, 0xffff0000, v111
	v_pk_add_f32 v[110:111], v[118:119], v[108:109]
	v_pk_add_f32 v[108:109], v[116:117], v[120:121]
	v_pk_add_f32 v[114:115], v[114:115], v[124:125]
	v_pk_add_f32 v[112:113], v[112:113], v[122:123]
	s_branch .LBB0_590

; __device__ __forceinline__ void ph_dt_tasks(Frame& F, int layer) {
;     ...
;     for (int it = bid; it < M / 32; it += F.G) {
;         const int row0 = 32 * it + 16 * (wave >> 2);
;         const bf16* ap = pA2 + (size_t)(row0 + r) * D + kq * 512 + 8 * g;
;         bf16x8 av[16];
; #pragma unroll
;         for (int ks = 0; ks < 16; ++ks) av[ks] = *(const bf16x8*)(ap + 32 * ks);
;         f32x4 a0 = {0.f, 0.f, 0.f, 0.f}, a1 = a0;
; #pragma unroll
;         for (int ks = 0; ks < 16; ++ks) { a0 = __builtin_amdgcn_mfma_f32_16x16x32_bf16(av[ks], wv0[ks], a0, 0, 0, 0); a1 = __builtin_amdgcn_mfma_f32_16x16x32_bf16(av[ks], wv1[ks], a1, 0, 0, 0); }
;         red[(wave * 2 + 0) * 64 + lane] = a0; red[(wave * 2 + 1) * 64 + lane] = a1;
;         __syncthreads();
;         if (kq == 0) {
; #pragma unroll
;             for (int k = 1; k < 4; ++k) { a0 += red[((wave + k) * 2 + 0) * 64 + lane]; a1 += red[((wave + k) * 2 + 1) * 64 + lane]; }
; #pragma unroll
;             for (int q = 0; q < 4; ++q) { float* o = pDT + (size_t)(row0 + 4 * g + q) * 32 + r; const float x0 = a0[q] + b0, x1 = a1[q] + b1;
;                 o[0] = fmaxf(x0, 0.f) + log1pf(__expf(-fabsf(x0))); o[16] = fmaxf(x1, 0.f) + log1pf(__expf(-fabsf(x1))); }
.LBB0_770:
	v_add_u32_e32 v132, s2, v140
	v_ashrrev_i32_e32 v133, 31, v132
	v_lshlrev_b64 v[132:133], 12, v[132:133]
	v_lshl_add_u64 v[152:153], v[142:143], 0, v[132:133]
	global_load_dwordx4 v[132:135], v[152:153], off
	global_load_dwordx4 v[146:149], v[152:153], off offset:64
	global_load_dwordx4 v[172:175], v[152:153], off offset:128
	global_load_dwordx4 v[176:179], v[152:153], off offset:192
	global_load_dwordx4 v[180:183], v[152:153], off offset:256
	global_load_dwordx4 v[184:187], v[152:153], off offset:320
	global_load_dwordx4 v[188:191], v[152:153], off offset:384
	global_load_dwordx4 v[192:195], v[152:153], off offset:448
	global_load_dwordx4 v[196:199], v[152:153], off offset:512
	global_load_dwordx4 v[200:203], v[152:153], off offset:576
	global_load_dwordx4 v[204:207], v[152:153], off offset:640
	global_load_dwordx4 v[208:211], v[152:153], off offset:704
	global_load_dwordx4 v[228:231], v[152:153], off offset:768
	global_load_dwordx4 v[232:235], v[152:153], off offset:832
	global_load_dwordx4 v[236:239], v[152:153], off offset:896
	global_load_dwordx4 v[244:247], v[152:153], off offset:960
	s_andn2_b64 vcc, exec, s[0:1]
	s_waitcnt vmcnt(14)
	v_mfma_f32_16x16x32_bf16 v[136:139], v[132:135], v[116:119], 0
	v_mfma_f32_16x16x32_bf16 v[132:135], v[132:135], v[4:7], 0
	v_mfma_f32_16x16x32_bf16 v[136:139], v[146:149], v[12:15], v[136:139]
	v_mfma_f32_16x16x32_bf16 v[132:135], v[146:149], v[8:11], v[132:135]
	s_waitcnt vmcnt(13)
	v_mfma_f32_16x16x32_bf16 v[136:139], v[172:175], v[16:19], v[136:139]
	v_mfma_f32_16x16x32_bf16 v[132:135], v[172:175], v[20:23], v[132:135]
	s_waitcnt vmcnt(12)
	v_mfma_f32_16x16x32_bf16 v[136:139], v[176:179], v[28:31], v[136:139]
	v_mfma_f32_16x16x32_bf16 v[132:135], v[176:179], v[24:27], v[132:135]
	s_waitcnt vmcnt(11)
	v_mfma_f32_16x16x32_bf16 v[136:139], v[180:183], v[32:35], v[136:139]
	v_mfma_f32_16x16x32_bf16 v[132:135], v[180:183], v[36:39], v[132:135]
	s_waitcnt vmcnt(10)
	v_mfma_f32_16x16x32_bf16 v[136:139], v[184:187], v[44:47], v[136:139]
	v_mfma_f32_16x16x32_bf16 v[132:135], v[184:187], v[40:43], v[132:135]
	s_waitcnt vmcnt(9)
	v_mfma_f32_16x16x32_bf16 v[136:139], v[188:191], v[48:51], v[136:139]
	v_mfma_f32_16x16x32_bf16 v[132:135], v[188:191], v[52:55], v[132:135]
	s_waitcnt vmcnt(8)
	v_mfma_f32_16x16x32_bf16 v[136:139], v[192:195], v[60:63], v[136:139]
	v_mfma_f32_16x16x32_bf16 v[132:135], v[192:195], v[56:59], v[132:135]
	s_waitcnt vmcnt(7)
	v_mfma_f32_16x16x32_bf16 v[136:139], v[196:199], v[64:67], v[136:139]
	v_mfma_f32_16x16x32_bf16 v[132:135], v[196:199], v[68:71], v[132:135]
	s_waitcnt vmcnt(6)
	v_mfma_f32_16x16x32_bf16 v[136:139], v[200:203], v[76:79], v[136:139]
	v_mfma_f32_16x16x32_bf16 v[132:135], v[200:203], v[72:75], v[132:135]
	s_waitcnt vmcnt(5)
	v_mfma_f32_16x16x32_bf16 v[136:139], v[204:207], v[80:83], v[136:139]
	v_mfma_f32_16x16x32_bf16 v[132:135], v[204:207], v[84:87], v[132:135]
	s_waitcnt vmcnt(4)
	v_mfma_f32_16x16x32_bf16 v[136:139], v[208:211], v[92:95], v[136:139]
	v_mfma_f32_16x16x32_bf16 v[132:135], v[208:211], v[88:91], v[132:135]
	s_waitcnt vmcnt(3)
	v_mfma_f32_16x16x32_bf16 v[136:139], v[228:231], v[96:99], v[136:139]
	v_mfma_f32_16x16x32_bf16 v[132:135], v[228:231], v[100:103], v[132:135]
	s_waitcnt vmcnt(2)
	v_mfma_f32_16x16x32_bf16 v[136:139], v[232:235], v[108:111], v[136:139]
	v_mfma_f32_16x16x32_bf16 v[132:135], v[232:235], v[104:107], v[132:135]
	s_waitcnt vmcnt(1)
	v_mfma_f32_16x16x32_bf16 v[136:139], v[236:239], v[112:115], v[136:139]
	v_mfma_f32_16x16x32_bf16 v[132:135], v[236:239], v[124:127], v[132:135]
	s_waitcnt vmcnt(0)
	v_mfma_f32_16x16x32_bf16 v[136:139], v[244:247], v[120:123], v[136:139]
	v_mfma_f32_16x16x32_bf16 v[132:135], v[244:247], v[128:131], v[132:135]
	s_nop 6
	ds_write_b128 v2, v[136:139]
	ds_write_b128 v2, v[132:135] offset:1024
	s_waitcnt lgkmcnt(0)
	s_barrier
	s_cbranch_vccnz .LBB0_769
	ds_read_b128 v[146:149], v2 offset:2048
	s_mov_b32 s3, 0xbfb8aa3b
	s_mov_b32 s4, 0x3f2aaaab
	s_mov_b32 s5, 0x3f317218
	s_mov_b32 s7, 0x7f800000
	s_waitcnt lgkmcnt(0)
	v_pk_add_f32 v[148:149], v[138:139], v[148:149]
	v_pk_add_f32 v[146:147], v[136:137], v[146:147]
	ds_read_b128 v[136:139], v2 offset:3072
	s_mov_b32 s8, 0x33800000
	s_waitcnt lgkmcnt(0)
	v_pk_add_f32 v[138:139], v[134:135], v[138:139]
	v_pk_add_f32 v[136:137], v[132:133], v[136:137]
	ds_read_b128 v[132:135], v2 offset:4096
	s_waitcnt lgkmcnt(0)
	v_pk_add_f32 v[148:149], v[148:149], v[134:135]
	v_pk_add_f32 v[146:147], v[146:147], v[132:133]
	ds_read_b128 v[132:135], v2 offset:5120
	s_waitcnt lgkmcnt(0)
	v_pk_add_f32 v[152:153], v[138:139], v[134:135]
	v_pk_add_f32 v[154:155], v[136:137], v[132:133]
	ds_read_b128 v[134:137], v2 offset:6144
	s_waitcnt lgkmcnt(0)
	v_pk_add_f32 v[132:133], v[148:149], v[136:137]
	v_pk_add_f32 v[138:139], v[146:147], v[134:135]
	ds_read_b128 v[146:149], v2 offset:7168
	v_add_u32_e32 v136, s2, v151
	v_ashrrev_i32_e32 v137, 31, v136
	v_add_f32_e32 v132, v141, v132
	s_waitcnt lgkmcnt(0)
; __device__ __forceinline__ void ph_dt_tasks(Frame& F, int layer) {
;     ...
;             for (int q = 0; q < 4; ++q) { float* o = pDT + (size_t)(row0 + 4 * g + q) * 32 + r; const float x0 = a0[q] + b0, x1 = a1[q] + b1;
;                 o[0] = fmaxf(x0, 0.f) + log1pf(__expf(-fabsf(x0))); o[16] = fmaxf(x1, 0.f) + log1pf(__expf(-fabsf(x1))); }
	v_pk_add_f32 v[134:135], v[152:153], v[148:149]
	v_pk_add_f32 v[146:147], v[154:155], v[146:147]
	v_lshlrev_b64 v[148:149], 7, v[136:137]
	v_add_f32_e32 v137, v141, v138
	v_add_f32_e32 v138, v150, v146
	v_max_f32_e32 v146, 0, v137
	v_mul_f32_e64 v137, |v137|, s3
	v_exp_f32_e32 v137, v137
	v_lshl_add_u64 v[148:149], v[144:145], 0, v[148:149]
	v_add_f32_e32 v134, v150, v134
	v_add_f32_e32 v154, 1.0, v137
	v_add_f32_e32 v152, -1.0, v154
	v_sub_f32_e32 v153, v152, v154
	v_add_f32_e32 v153, 1.0, v153
	v_sub_f32_e32 v152, v137, v152
	v_add_f32_e32 v155, v152, v153
	v_frexp_mant_f32_e32 v152, v154
	v_cmp_gt_f32_e32 vcc, s4, v152
	v_cvt_f64_f32_e32 v[152:153], v154
	v_frexp_exp_i32_f64_e32 v152, v[152:153]
	v_subbrev_co_u32_e32 v152, vcc, 0, v152, vcc
	v_sub_u32_e32 v153, 0, v152
	v_ldexp_f32 v154, v154, v153
	v_ldexp_f32 v153, v155, v153
	v_add_f32_e32 v155, -1.0, v154
	v_add_f32_e32 v156, 1.0, v155
	v_sub_f32_e32 v156, v154, v156
	v_add_f32_e32 v156, v153, v156
	v_add_f32_e32 v157, v155, v156
	v_sub_f32_e32 v155, v157, v155
	v_sub_f32_e32 v155, v156, v155
	v_add_f32_e32 v156, 1.0, v154
	v_add_f32_e32 v158, -1.0, v156
	v_sub_f32_e32 v154, v154, v158
	v_add_f32_e32 v153, v153, v154
	v_add_f32_e32 v154, v156, v153
	v_sub_f32_e32 v156, v154, v156
	v_sub_f32_e32 v153, v153, v156
	v_rcp_f32_e32 v156, v154
	v_cvt_f32_i32_e32 v152, v152
	v_cmp_neq_f32_e32 vcc, s7, v137
	v_mul_f32_e32 v158, v157, v156
	v_mul_f32_e32 v159, v154, v158
	v_fma_f32 v160, v158, v154, -v159
	v_fmac_f32_e32 v160, v158, v153
	v_add_f32_e32 v161, v159, v160
	v_sub_f32_e32 v162, v157, v161
	v_sub_f32_e32 v157, v157, v162
	v_sub_f32_e32 v159, v161, v159
	v_sub_f32_e32 v157, v157, v161
	v_add_f32_e32 v155, v155, v157
	v_sub_f32_e32 v157, v159, v160
	v_add_f32_e32 v155, v157, v155
	v_add_f32_e32 v157, v162, v155
	v_mul_f32_e32 v159, v156, v157
	v_mul_f32_e32 v160, v154, v159
	v_fma_f32 v154, v159, v154, -v160
	v_fmac_f32_e32 v154, v159, v153
	v_sub_f32_e32 v153, v162, v157
	v_add_f32_e32 v153, v155, v153
	v_add_f32_e32 v155, v160, v154
	v_sub_f32_e32 v161, v157, v155
	v_sub_f32_e32 v157, v157, v161
	v_sub_f32_e32 v160, v155, v160
	v_sub_f32_e32 v155, v157, v155
	v_add_f32_e32 v153, v153, v155
	v_sub_f32_e32 v154, v160, v154
	v_add_f32_e32 v153, v154, v153
	v_add_f32_e32 v154, v158, v159
	v_add_f32_e32 v153, v161, v153
	v_sub_f32_e32 v155, v154, v158
	v_mul_f32_e32 v153, v156, v153
	v_sub_f32_e32 v155, v159, v155
	v_add_f32_e32 v153, v155, v153
	v_mul_f32_e32 v158, 0x3f317218, v152
	v_add_f32_e32 v155, v154, v153
	v_fma_f32 v159, v152, s5, -v158
	v_mul_f32_e32 v156, v155, v155
	v_fmac_f32_e32 v159, 0xb102e308, v152
	v_sub_f32_e32 v152, v155, v154
	v_fmamk_f32 v157, v156, 0x3e9b6dac, v215
	v_sub_f32_e32 v152, v153, v152
	v_add_f32_e32 v153, v158, v159
	v_fmaak_f32 v157, v156, v157, 0x3f2aaada
	v_sub_f32_e32 v154, v153, v158
	v_ldexp_f32 v158, v155, 1
	v_mul_f32_e32 v155, v155, v156
	v_mul_f32_e32 v155, v155, v157
	v_add_f32_e32 v156, v158, v155
	v_sub_f32_e32 v157, v156, v158
	v_ldexp_f32 v152, v152, 1
	v_sub_f32_e32 v155, v155, v157
	v_add_f32_e32 v152, v152, v155
	v_add_f32_e32 v155, v156, v152
	v_sub_f32_e32 v156, v155, v156
	v_sub_f32_e32 v152, v152, v156
	v_add_f32_e32 v156, v153, v155
	v_sub_f32_e32 v157, v156, v153
	v_sub_f32_e32 v158, v156, v157
	v_sub_f32_e32 v154, v159, v154
	v_sub_f32_e32 v153, v153, v158
	v_sub_f32_e32 v155, v155, v157
	v_add_f32_e32 v153, v155, v153
	v_add_f32_e32 v155, v154, v152
	v_sub_f32_e32 v157, v155, v154
	v_sub_f32_e32 v158, v155, v157
	v_sub_f32_e32 v154, v154, v158
	v_sub_f32_e32 v152, v152, v157
	v_add_f32_e32 v153, v155, v153
	v_add_f32_e32 v152, v152, v154
	v_add_f32_e32 v154, v156, v153
	v_sub_f32_e32 v155, v154, v156
	v_sub_f32_e32 v153, v153, v155
	v_add_f32_e32 v152, v152, v153
	v_add_f32_e32 v152, v154, v152
	v_cndmask_b32_e32 v152, v217, v152, vcc
	v_cmp_ngt_f32_e32 vcc, -1.0, v137
	s_nop 1
	v_cndmask_b32_e32 v152, v218, v152, vcc
	v_cmp_neq_f32_e32 vcc, -1.0, v137
	s_nop 1
	v_cndmask_b32_e32 v152, v219, v152, vcc
	v_cmp_lt_f32_e64 vcc, |v137|, s8
	s_nop 1
	v_cndmask_b32_e32 v137, v152, v137, vcc
	v_add_f32_e32 v137, v146, v137
	global_store_dword v[148:149], v137, off
	v_max_f32_e32 v137, 0, v138
	v_mul_f32_e64 v138, |v138|, s3
	v_exp_f32_e32 v138, v138
	s_nop 0
	v_add_f32_e32 v146, 1.0, v138
	v_add_f32_e32 v152, -1.0, v146
	v_sub_f32_e32 v153, v152, v146
	v_add_f32_e32 v153, 1.0, v153
	v_sub_f32_e32 v152, v138, v152
	v_add_f32_e32 v154, v152, v153
	v_frexp_mant_f32_e32 v152, v146
	v_cmp_gt_f32_e32 vcc, s4, v152
	v_cvt_f64_f32_e32 v[152:153], v146
	v_frexp_exp_i32_f64_e32 v152, v[152:153]
	v_subbrev_co_u32_e32 v152, vcc, 0, v152, vcc
	v_sub_u32_e32 v153, 0, v152
	v_ldexp_f32 v146, v146, v153
	v_ldexp_f32 v153, v154, v153
	v_add_f32_e32 v154, -1.0, v146
	v_add_f32_e32 v155, 1.0, v154
	v_sub_f32_e32 v155, v146, v155
	v_add_f32_e32 v155, v153, v155
	v_add_f32_e32 v156, v154, v155
	v_sub_f32_e32 v154, v156, v154
	v_sub_f32_e32 v154, v155, v154
	v_add_f32_e32 v155, 1.0, v146
	v_add_f32_e32 v157, -1.0, v155
	v_sub_f32_e32 v146, v146, v157
	v_add_f32_e32 v146, v153, v146
	v_add_f32_e32 v153, v155, v146
	v_sub_f32_e32 v155, v153, v155
	v_sub_f32_e32 v146, v146, v155
	v_rcp_f32_e32 v155, v153
	v_cvt_f32_i32_e32 v152, v152
	v_cmp_neq_f32_e32 vcc, s7, v138
	v_mul_f32_e32 v157, v156, v155
	v_mul_f32_e32 v158, v153, v157
	v_fma_f32 v159, v157, v153, -v158
	v_fmac_f32_e32 v159, v157, v146
	v_add_f32_e32 v160, v158, v159
	v_sub_f32_e32 v161, v156, v160
	v_sub_f32_e32 v156, v156, v161
	v_sub_f32_e32 v158, v160, v158
	v_sub_f32_e32 v156, v156, v160
	v_add_f32_e32 v154, v154, v156
	v_sub_f32_e32 v156, v158, v159
	v_add_f32_e32 v154, v156, v154
; __device__ __forceinline__ void ph_dt_tasks(Frame& F, int layer) {
;     ...
;             for (int q = 0; q < 4; ++q) { float* o = pDT + (size_t)(row0 + 4 * g + q) * 32 + r; const float x0 = a0[q] + b0, x1 = a1[q] + b1;
;                 o[0] = fmaxf(x0, 0.f) + log1pf(__expf(-fabsf(x0))); o[16] = fmaxf(x1, 0.f) + log1pf(__expf(-fabsf(x1))); }
	v_add_f32_e32 v156, v161, v154
	v_mul_f32_e32 v158, v155, v156
	v_mul_f32_e32 v159, v153, v158
	v_fma_f32 v153, v158, v153, -v159
	v_fmac_f32_e32 v153, v158, v146
	v_sub_f32_e32 v146, v161, v156
	v_add_f32_e32 v146, v154, v146
	v_add_f32_e32 v154, v159, v153
	v_sub_f32_e32 v160, v156, v154
	v_sub_f32_e32 v156, v156, v160
	v_sub_f32_e32 v159, v154, v159
	v_sub_f32_e32 v154, v156, v154
	v_add_f32_e32 v146, v146, v154
	v_sub_f32_e32 v153, v159, v153
	v_add_f32_e32 v146, v153, v146
	v_add_f32_e32 v153, v157, v158
	v_add_f32_e32 v146, v160, v146
	v_sub_f32_e32 v154, v153, v157
	v_mul_f32_e32 v146, v155, v146
	v_sub_f32_e32 v154, v158, v154
	v_add_f32_e32 v146, v154, v146
	v_mul_f32_e32 v157, 0x3f317218, v152
	v_add_f32_e32 v154, v153, v146
	v_fma_f32 v158, v152, s5, -v157
	v_mul_f32_e32 v155, v154, v154
	v_fmac_f32_e32 v158, 0xb102e308, v152
	v_sub_f32_e32 v152, v154, v153
	v_fmamk_f32 v156, v155, 0x3e9b6dac, v215
	v_sub_f32_e32 v146, v146, v152
	v_add_f32_e32 v152, v157, v158
	v_fmaak_f32 v156, v155, v156, 0x3f2aaada
	v_sub_f32_e32 v153, v152, v157
	v_ldexp_f32 v157, v154, 1
	v_mul_f32_e32 v154, v154, v155
	v_mul_f32_e32 v154, v154, v156
	v_add_f32_e32 v155, v157, v154
	v_sub_f32_e32 v156, v155, v157
	v_ldexp_f32 v146, v146, 1
	v_sub_f32_e32 v154, v154, v156
	v_add_f32_e32 v146, v146, v154
	v_add_f32_e32 v154, v155, v146
	v_sub_f32_e32 v155, v154, v155
	v_sub_f32_e32 v146, v146, v155
	v_add_f32_e32 v155, v152, v154
	v_sub_f32_e32 v156, v155, v152
	v_sub_f32_e32 v157, v155, v156
	v_sub_f32_e32 v153, v158, v153
	v_sub_f32_e32 v152, v152, v157
	v_sub_f32_e32 v154, v154, v156
	v_add_f32_e32 v152, v154, v152
	v_add_f32_e32 v154, v153, v146
	v_sub_f32_e32 v156, v154, v153
	v_sub_f32_e32 v157, v154, v156
	v_sub_f32_e32 v153, v153, v157
	v_sub_f32_e32 v146, v146, v156
	v_add_f32_e32 v152, v154, v152
	v_add_f32_e32 v146, v146, v153
	v_add_f32_e32 v153, v155, v152
	v_sub_f32_e32 v154, v153, v155
	v_sub_f32_e32 v152, v152, v154
	v_add_f32_e32 v146, v146, v152
	v_add_f32_e32 v146, v153, v146
	v_cndmask_b32_e32 v146, v217, v146, vcc
	v_cmp_ngt_f32_e32 vcc, -1.0, v138
	s_nop 1
	v_cndmask_b32_e32 v146, v218, v146, vcc
	v_cmp_neq_f32_e32 vcc, -1.0, v138
	s_nop 1
	v_cndmask_b32_e32 v146, v219, v146, vcc
	v_cmp_lt_f32_e64 vcc, |v138|, s8
	s_nop 1
	v_cndmask_b32_e32 v138, v146, v138, vcc
	v_add_f32_e32 v137, v137, v138
	global_store_dword v[148:149], v137, off offset:64
	v_add_f32_e32 v137, v141, v139
	v_add_f32_e32 v146, v150, v147
	v_max_f32_e32 v147, 0, v137
	v_mul_f32_e64 v137, |v137|, s3
	v_exp_f32_e32 v137, v137
	v_add_u32_e32 v148, 1, v136
	v_ashrrev_i32_e32 v149, 31, v148
	v_lshlrev_b64 v[148:149], 7, v[148:149]
	v_add_f32_e32 v152, 1.0, v137
	v_add_f32_e32 v138, -1.0, v152
	v_sub_f32_e32 v139, v138, v152
	v_add_f32_e32 v139, 1.0, v139
	v_sub_f32_e32 v138, v137, v138
	v_add_f32_e32 v153, v138, v139
	v_frexp_mant_f32_e32 v138, v152
	v_cmp_gt_f32_e32 vcc, s4, v138
	v_cvt_f64_f32_e32 v[138:139], v152
	v_frexp_exp_i32_f64_e32 v138, v[138:139]
	v_subbrev_co_u32_e32 v138, vcc, 0, v138, vcc
	v_sub_u32_e32 v139, 0, v138
	v_ldexp_f32 v152, v152, v139
	v_ldexp_f32 v139, v153, v139
	v_add_f32_e32 v153, -1.0, v152
	v_add_f32_e32 v154, 1.0, v153
	v_sub_f32_e32 v154, v152, v154
	v_add_f32_e32 v154, v139, v154
	v_add_f32_e32 v155, v153, v154
	v_sub_f32_e32 v153, v155, v153
	v_sub_f32_e32 v153, v154, v153
	v_add_f32_e32 v154, 1.0, v152
	v_add_f32_e32 v156, -1.0, v154
	v_sub_f32_e32 v152, v152, v156
	v_add_f32_e32 v139, v139, v152
	v_add_f32_e32 v152, v154, v139
	v_sub_f32_e32 v154, v152, v154
	v_sub_f32_e32 v139, v139, v154
	v_rcp_f32_e32 v154, v152
	v_cvt_f32_i32_e32 v138, v138
	v_cmp_neq_f32_e32 vcc, s7, v137
	v_lshl_add_u64 v[148:149], v[144:145], 0, v[148:149]
	v_mul_f32_e32 v156, v155, v154
	v_mul_f32_e32 v157, v152, v156
	v_fma_f32 v158, v156, v152, -v157
	v_fmac_f32_e32 v158, v156, v139
	v_add_f32_e32 v159, v157, v158
	v_sub_f32_e32 v160, v155, v159
	v_sub_f32_e32 v155, v155, v160
	v_sub_f32_e32 v157, v159, v157
	v_sub_f32_e32 v155, v155, v159
	v_add_f32_e32 v153, v153, v155
	v_sub_f32_e32 v155, v157, v158
	v_add_f32_e32 v153, v155, v153
	v_add_f32_e32 v155, v160, v153
	v_mul_f32_e32 v157, v154, v155
	v_mul_f32_e32 v158, v152, v157
	v_fma_f32 v152, v157, v152, -v158
	v_fmac_f32_e32 v152, v157, v139
	v_sub_f32_e32 v139, v160, v155
	v_add_f32_e32 v139, v153, v139
	v_add_f32_e32 v153, v158, v152
	v_sub_f32_e32 v159, v155, v153
	v_sub_f32_e32 v155, v155, v159
	v_sub_f32_e32 v158, v153, v158
	v_sub_f32_e32 v153, v155, v153
	v_add_f32_e32 v139, v139, v153
	v_sub_f32_e32 v152, v158, v152
	v_add_f32_e32 v139, v152, v139
	v_add_f32_e32 v152, v156, v157
	v_add_f32_e32 v139, v159, v139
	v_sub_f32_e32 v153, v152, v156
	v_mul_f32_e32 v139, v154, v139
	v_sub_f32_e32 v153, v157, v153
	v_add_f32_e32 v139, v153, v139
	v_mul_f32_e32 v156, 0x3f317218, v138
	v_add_f32_e32 v153, v152, v139
	v_fma_f32 v157, v138, s5, -v156
	v_mul_f32_e32 v154, v153, v153
	v_fmac_f32_e32 v157, 0xb102e308, v138
	v_sub_f32_e32 v138, v153, v152
	v_fmamk_f32 v155, v154, 0x3e9b6dac, v215
	v_sub_f32_e32 v138, v139, v138
	v_add_f32_e32 v139, v156, v157
	v_fmaak_f32 v155, v154, v155, 0x3f2aaada
	v_sub_f32_e32 v152, v139, v156
	v_ldexp_f32 v156, v153, 1
	v_mul_f32_e32 v153, v153, v154
	v_mul_f32_e32 v153, v153, v155
	v_add_f32_e32 v154, v156, v153
	v_sub_f32_e32 v155, v154, v156
	v_ldexp_f32 v138, v138, 1
	v_sub_f32_e32 v153, v153, v155
	v_add_f32_e32 v138, v138, v153
	v_add_f32_e32 v153, v154, v138
	v_sub_f32_e32 v154, v153, v154
	v_sub_f32_e32 v138, v138, v154
	v_add_f32_e32 v154, v139, v153
	v_sub_f32_e32 v155, v154, v139
	v_sub_f32_e32 v156, v154, v155
	v_sub_f32_e32 v152, v157, v152
	v_sub_f32_e32 v139, v139, v156
; __device__ __forceinline__ void ph_dt_tasks(Frame& F, int layer) {
;     ...
;             for (int q = 0; q < 4; ++q) { float* o = pDT + (size_t)(row0 + 4 * g + q) * 32 + r; const float x0 = a0[q] + b0, x1 = a1[q] + b1;
;                 o[0] = fmaxf(x0, 0.f) + log1pf(__expf(-fabsf(x0))); o[16] = fmaxf(x1, 0.f) + log1pf(__expf(-fabsf(x1))); }
	v_sub_f32_e32 v153, v153, v155
	v_add_f32_e32 v139, v153, v139
	v_add_f32_e32 v153, v152, v138
	v_sub_f32_e32 v155, v153, v152
	v_sub_f32_e32 v156, v153, v155
	v_sub_f32_e32 v152, v152, v156
	v_sub_f32_e32 v138, v138, v155
	v_add_f32_e32 v139, v153, v139
	v_add_f32_e32 v138, v138, v152
	v_add_f32_e32 v152, v154, v139
	v_sub_f32_e32 v153, v152, v154
	v_sub_f32_e32 v139, v139, v153
	v_add_f32_e32 v138, v138, v139
	v_add_f32_e32 v138, v152, v138
	v_cndmask_b32_e32 v138, v217, v138, vcc
	v_cmp_ngt_f32_e32 vcc, -1.0, v137
	s_nop 1
	v_cndmask_b32_e32 v138, v218, v138, vcc
	v_cmp_neq_f32_e32 vcc, -1.0, v137
	s_nop 1
	v_cndmask_b32_e32 v138, v219, v138, vcc
	v_cmp_lt_f32_e64 vcc, |v137|, s8
	s_nop 1
	v_cndmask_b32_e32 v137, v138, v137, vcc
	v_add_f32_e32 v137, v147, v137
	v_mul_f32_e64 v138, |v146|, s3
	global_store_dword v[148:149], v137, off
	v_max_f32_e32 v137, 0, v146
	v_exp_f32_e32 v146, v138
	s_nop 0
	v_add_f32_e32 v147, 1.0, v146
	v_add_f32_e32 v138, -1.0, v147
	v_sub_f32_e32 v139, v138, v147
	v_add_f32_e32 v139, 1.0, v139
	v_sub_f32_e32 v138, v146, v138
	v_add_f32_e32 v152, v138, v139
	v_frexp_mant_f32_e32 v138, v147
	v_cmp_gt_f32_e32 vcc, s4, v138
	v_cvt_f64_f32_e32 v[138:139], v147
	v_frexp_exp_i32_f64_e32 v138, v[138:139]
	v_subbrev_co_u32_e32 v138, vcc, 0, v138, vcc
	v_sub_u32_e32 v139, 0, v138
	v_ldexp_f32 v147, v147, v139
	v_ldexp_f32 v139, v152, v139
	v_add_f32_e32 v152, -1.0, v147
	v_add_f32_e32 v153, 1.0, v152
	v_sub_f32_e32 v153, v147, v153
	v_add_f32_e32 v153, v139, v153
	v_add_f32_e32 v154, v152, v153
	v_sub_f32_e32 v152, v154, v152
	v_sub_f32_e32 v152, v153, v152
	v_add_f32_e32 v153, 1.0, v147
	v_add_f32_e32 v155, -1.0, v153
	v_sub_f32_e32 v147, v147, v155
	v_add_f32_e32 v139, v139, v147
	v_add_f32_e32 v147, v153, v139
	v_sub_f32_e32 v153, v147, v153
	v_sub_f32_e32 v139, v139, v153
	v_rcp_f32_e32 v153, v147
	v_cvt_f32_i32_e32 v138, v138
	v_cmp_neq_f32_e32 vcc, s7, v146
	v_mul_f32_e32 v155, v154, v153
	v_mul_f32_e32 v156, v147, v155
	v_fma_f32 v157, v155, v147, -v156
	v_fmac_f32_e32 v157, v155, v139
	v_add_f32_e32 v158, v156, v157
	v_sub_f32_e32 v159, v154, v158
	v_sub_f32_e32 v154, v154, v159
	v_sub_f32_e32 v156, v158, v156
	v_sub_f32_e32 v154, v154, v158
	v_add_f32_e32 v152, v152, v154
	v_sub_f32_e32 v154, v156, v157
	v_add_f32_e32 v152, v154, v152
	v_add_f32_e32 v154, v159, v152
	v_mul_f32_e32 v156, v153, v154
	v_mul_f32_e32 v157, v147, v156
	v_fma_f32 v147, v156, v147, -v157
	v_fmac_f32_e32 v147, v156, v139
	v_sub_f32_e32 v139, v159, v154
	v_add_f32_e32 v139, v152, v139
	v_add_f32_e32 v152, v157, v147
	v_sub_f32_e32 v158, v154, v152
	v_sub_f32_e32 v154, v154, v158
	v_sub_f32_e32 v157, v152, v157
	v_sub_f32_e32 v152, v154, v152
	v_add_f32_e32 v139, v139, v152
	v_sub_f32_e32 v147, v157, v147
	v_add_f32_e32 v139, v147, v139
	v_add_f32_e32 v147, v155, v156
	v_add_f32_e32 v139, v158, v139
	v_sub_f32_e32 v152, v147, v155
	v_mul_f32_e32 v139, v153, v139
	v_sub_f32_e32 v152, v156, v152
	v_add_f32_e32 v139, v152, v139
	v_mul_f32_e32 v155, 0x3f317218, v138
	v_add_f32_e32 v152, v147, v139
	v_fma_f32 v156, v138, s5, -v155
	v_mul_f32_e32 v153, v152, v152
	v_fmac_f32_e32 v156, 0xb102e308, v138
	v_sub_f32_e32 v138, v152, v147
	v_fmamk_f32 v154, v153, 0x3e9b6dac, v215
	v_sub_f32_e32 v138, v139, v138
	v_add_f32_e32 v139, v155, v156
	v_fmaak_f32 v154, v153, v154, 0x3f2aaada
	v_sub_f32_e32 v147, v139, v155
	v_ldexp_f32 v155, v152, 1
	v_mul_f32_e32 v152, v152, v153
	v_mul_f32_e32 v152, v152, v154
	v_add_f32_e32 v153, v155, v152
	v_sub_f32_e32 v154, v153, v155
	v_ldexp_f32 v138, v138, 1
	v_sub_f32_e32 v152, v152, v154
	v_add_f32_e32 v138, v138, v152
	v_add_f32_e32 v152, v153, v138
	v_sub_f32_e32 v153, v152, v153
	v_sub_f32_e32 v138, v138, v153
	v_add_f32_e32 v153, v139, v152
	v_sub_f32_e32 v154, v153, v139
	v_sub_f32_e32 v155, v153, v154
	v_sub_f32_e32 v147, v156, v147
	v_sub_f32_e32 v139, v139, v155
	v_sub_f32_e32 v152, v152, v154
	v_add_f32_e32 v139, v152, v139
	v_add_f32_e32 v152, v147, v138
	v_sub_f32_e32 v154, v152, v147
	v_sub_f32_e32 v155, v152, v154
	v_sub_f32_e32 v147, v147, v155
	v_sub_f32_e32 v138, v138, v154
	v_add_f32_e32 v139, v152, v139
	v_add_f32_e32 v138, v138, v147
	v_add_f32_e32 v147, v153, v139
	v_sub_f32_e32 v152, v147, v153
	v_sub_f32_e32 v139, v139, v152
	v_add_f32_e32 v138, v138, v139
	v_add_f32_e32 v138, v147, v138
	v_cndmask_b32_e32 v138, v217, v138, vcc
	v_cmp_ngt_f32_e32 vcc, -1.0, v146
	s_nop 1
	v_cndmask_b32_e32 v138, v218, v138, vcc
	v_cmp_neq_f32_e32 vcc, -1.0, v146
	s_nop 1
	v_cndmask_b32_e32 v138, v219, v138, vcc
	v_cmp_lt_f32_e64 vcc, |v146|, s8
	s_nop 1
	v_cndmask_b32_e32 v138, v138, v146, vcc
	v_add_f32_e32 v137, v137, v138
	global_store_dword v[148:149], v137, off offset:64
	v_max_f32_e32 v137, 0, v132
	v_mul_f32_e64 v132, |v132|, s3
	v_exp_f32_e32 v132, v132
	v_add_u32_e32 v138, 2, v136
	v_ashrrev_i32_e32 v139, 31, v138
	v_lshlrev_b64 v[138:139], 7, v[138:139]
	v_add_f32_e32 v148, 1.0, v132
	v_add_f32_e32 v146, -1.0, v148
	v_sub_f32_e32 v147, v146, v148
	v_add_f32_e32 v147, 1.0, v147
	v_sub_f32_e32 v146, v132, v146
	v_add_f32_e32 v149, v146, v147
	v_frexp_mant_f32_e32 v146, v148
	v_cmp_gt_f32_e32 vcc, s4, v146
	v_cvt_f64_f32_e32 v[146:147], v148
	v_frexp_exp_i32_f64_e32 v146, v[146:147]
	v_subbrev_co_u32_e32 v146, vcc, 0, v146, vcc
	v_sub_u32_e32 v147, 0, v146
	v_ldexp_f32 v148, v148, v147
	v_ldexp_f32 v147, v149, v147
	v_add_f32_e32 v149, -1.0, v148
	v_add_f32_e32 v152, 1.0, v149
	v_sub_f32_e32 v152, v148, v152
	v_add_f32_e32 v152, v147, v152
	v_add_f32_e32 v153, v149, v152
	v_sub_f32_e32 v149, v153, v149
	v_sub_f32_e32 v149, v152, v149
	v_add_f32_e32 v152, 1.0, v148
	v_add_f32_e32 v154, -1.0, v152
; __device__ __forceinline__ void ph_dt_tasks(Frame& F, int layer) {
;     ...
;             for (int q = 0; q < 4; ++q) { float* o = pDT + (size_t)(row0 + 4 * g + q) * 32 + r; const float x0 = a0[q] + b0, x1 = a1[q] + b1;
;                 o[0] = fmaxf(x0, 0.f) + log1pf(__expf(-fabsf(x0))); o[16] = fmaxf(x1, 0.f) + log1pf(__expf(-fabsf(x1))); }
	v_sub_f32_e32 v148, v148, v154
	v_add_f32_e32 v147, v147, v148
	v_add_f32_e32 v148, v152, v147
	v_sub_f32_e32 v152, v148, v152
	v_sub_f32_e32 v147, v147, v152
	v_rcp_f32_e32 v152, v148
	v_cvt_f32_i32_e32 v146, v146
	v_cmp_neq_f32_e32 vcc, s7, v132
	v_lshl_add_u64 v[138:139], v[144:145], 0, v[138:139]
	v_mul_f32_e32 v154, v153, v152
	v_mul_f32_e32 v155, v148, v154
	v_fma_f32 v156, v154, v148, -v155
	v_fmac_f32_e32 v156, v154, v147
	v_add_f32_e32 v157, v155, v156
	v_sub_f32_e32 v158, v153, v157
	v_sub_f32_e32 v153, v153, v158
	v_sub_f32_e32 v155, v157, v155
	v_sub_f32_e32 v153, v153, v157
	v_add_f32_e32 v149, v149, v153
	v_sub_f32_e32 v153, v155, v156
	v_add_f32_e32 v149, v153, v149
	v_add_f32_e32 v153, v158, v149
	v_mul_f32_e32 v155, v152, v153
	v_mul_f32_e32 v156, v148, v155
	v_fma_f32 v148, v155, v148, -v156
	v_fmac_f32_e32 v148, v155, v147
	v_sub_f32_e32 v147, v158, v153
	v_add_f32_e32 v147, v149, v147
	v_add_f32_e32 v149, v156, v148
	v_sub_f32_e32 v157, v153, v149
	v_sub_f32_e32 v153, v153, v157
	v_sub_f32_e32 v156, v149, v156
	v_sub_f32_e32 v149, v153, v149
	v_add_f32_e32 v147, v147, v149
	v_sub_f32_e32 v148, v156, v148
	v_add_f32_e32 v147, v148, v147
	v_add_f32_e32 v148, v154, v155
	v_add_f32_e32 v147, v157, v147
	v_sub_f32_e32 v149, v148, v154
	v_mul_f32_e32 v147, v152, v147
	v_sub_f32_e32 v149, v155, v149
	v_add_f32_e32 v147, v149, v147
	v_mul_f32_e32 v154, 0x3f317218, v146
	v_add_f32_e32 v149, v148, v147
	v_fma_f32 v155, v146, s5, -v154
	v_mul_f32_e32 v152, v149, v149
	v_fmac_f32_e32 v155, 0xb102e308, v146
	v_sub_f32_e32 v146, v149, v148
	v_fmamk_f32 v153, v152, 0x3e9b6dac, v215
	v_sub_f32_e32 v146, v147, v146
	v_add_f32_e32 v147, v154, v155
	v_fmaak_f32 v153, v152, v153, 0x3f2aaada
	v_sub_f32_e32 v148, v147, v154
	v_ldexp_f32 v154, v149, 1
	v_mul_f32_e32 v149, v149, v152
	v_mul_f32_e32 v149, v149, v153
	v_add_f32_e32 v152, v154, v149
	v_sub_f32_e32 v153, v152, v154
	v_ldexp_f32 v146, v146, 1
	v_sub_f32_e32 v149, v149, v153
	v_add_f32_e32 v146, v146, v149
	v_add_f32_e32 v149, v152, v146
	v_sub_f32_e32 v152, v149, v152
	v_sub_f32_e32 v146, v146, v152
	v_add_f32_e32 v152, v147, v149
	v_sub_f32_e32 v153, v152, v147
	v_sub_f32_e32 v154, v152, v153
	v_sub_f32_e32 v148, v155, v148
	v_sub_f32_e32 v147, v147, v154
	v_sub_f32_e32 v149, v149, v153
	v_add_f32_e32 v147, v149, v147
	v_add_f32_e32 v149, v148, v146
	v_sub_f32_e32 v153, v149, v148
	v_sub_f32_e32 v154, v149, v153
	v_sub_f32_e32 v148, v148, v154
	v_sub_f32_e32 v146, v146, v153
	v_add_f32_e32 v147, v149, v147
	v_add_f32_e32 v146, v146, v148
	v_add_f32_e32 v148, v152, v147
	v_sub_f32_e32 v149, v148, v152
	v_sub_f32_e32 v147, v147, v149
	v_add_f32_e32 v146, v146, v147
	v_add_f32_e32 v146, v148, v146
	v_cndmask_b32_e32 v146, v217, v146, vcc
	v_cmp_ngt_f32_e32 vcc, -1.0, v132
	v_add_u32_e32 v136, 3, v136
	s_nop 0
	v_cndmask_b32_e32 v146, v218, v146, vcc
	v_cmp_neq_f32_e32 vcc, -1.0, v132
	s_nop 1
	v_cndmask_b32_e32 v146, v219, v146, vcc
	v_cmp_lt_f32_e64 vcc, |v132|, s8
	s_nop 1
	v_cndmask_b32_e32 v132, v146, v132, vcc
	v_add_f32_e32 v132, v137, v132
	global_store_dword v[138:139], v132, off
	v_max_f32_e32 v132, 0, v134
	v_mul_f32_e64 v134, |v134|, s3
	v_exp_f32_e32 v134, v134
	s_nop 0
	v_add_f32_e32 v137, 1.0, v134
	v_add_f32_e32 v146, -1.0, v137
	v_sub_f32_e32 v147, v146, v137
	v_add_f32_e32 v147, 1.0, v147
	v_sub_f32_e32 v146, v134, v146
	v_add_f32_e32 v148, v146, v147
	v_frexp_mant_f32_e32 v146, v137
	v_cmp_gt_f32_e32 vcc, s4, v146
	v_cvt_f64_f32_e32 v[146:147], v137
	v_frexp_exp_i32_f64_e32 v146, v[146:147]
	v_subbrev_co_u32_e32 v146, vcc, 0, v146, vcc
	v_sub_u32_e32 v147, 0, v146
	v_ldexp_f32 v137, v137, v147
	v_ldexp_f32 v147, v148, v147
	v_add_f32_e32 v148, -1.0, v137
	v_add_f32_e32 v149, 1.0, v148
	v_sub_f32_e32 v149, v137, v149
	v_add_f32_e32 v149, v147, v149
	v_add_f32_e32 v152, v148, v149
	v_sub_f32_e32 v148, v152, v148
	v_sub_f32_e32 v148, v149, v148
	v_add_f32_e32 v149, 1.0, v137
	v_add_f32_e32 v153, -1.0, v149
	v_sub_f32_e32 v137, v137, v153
	v_add_f32_e32 v137, v147, v137
	v_add_f32_e32 v147, v149, v137
	v_sub_f32_e32 v149, v147, v149
	v_sub_f32_e32 v137, v137, v149
	v_rcp_f32_e32 v149, v147
	v_cvt_f32_i32_e32 v146, v146
	v_cmp_neq_f32_e32 vcc, s7, v134
	v_mul_f32_e32 v153, v152, v149
	v_mul_f32_e32 v154, v147, v153
	v_fma_f32 v155, v153, v147, -v154
	v_fmac_f32_e32 v155, v153, v137
	v_add_f32_e32 v156, v154, v155
	v_sub_f32_e32 v157, v152, v156
	v_sub_f32_e32 v152, v152, v157
	v_sub_f32_e32 v154, v156, v154
	v_sub_f32_e32 v152, v152, v156
	v_add_f32_e32 v148, v148, v152
	v_sub_f32_e32 v152, v154, v155
	v_add_f32_e32 v148, v152, v148
	v_add_f32_e32 v152, v157, v148
	v_mul_f32_e32 v154, v149, v152
	v_mul_f32_e32 v155, v147, v154
	v_fma_f32 v147, v154, v147, -v155
	v_fmac_f32_e32 v147, v154, v137
	v_sub_f32_e32 v137, v157, v152
	v_add_f32_e32 v137, v148, v137
	v_add_f32_e32 v148, v155, v147
	v_sub_f32_e32 v156, v152, v148
	v_sub_f32_e32 v152, v152, v156
	v_sub_f32_e32 v155, v148, v155
	v_sub_f32_e32 v148, v152, v148
	v_add_f32_e32 v137, v137, v148
	v_sub_f32_e32 v147, v155, v147
	v_add_f32_e32 v137, v147, v137
	v_add_f32_e32 v147, v153, v154
	v_add_f32_e32 v137, v156, v137
	v_sub_f32_e32 v148, v147, v153
	v_mul_f32_e32 v137, v149, v137
	v_sub_f32_e32 v148, v154, v148
	v_add_f32_e32 v137, v148, v137
	v_mul_f32_e32 v153, 0x3f317218, v146
	v_add_f32_e32 v148, v147, v137
	v_fma_f32 v154, v146, s5, -v153
	v_mul_f32_e32 v149, v148, v148
	v_fmac_f32_e32 v154, 0xb102e308, v146
	v_sub_f32_e32 v146, v148, v147
	v_fmamk_f32 v152, v149, 0x3e9b6dac, v215
	v_sub_f32_e32 v137, v137, v146
	v_add_f32_e32 v146, v153, v154
	v_fmaak_f32 v152, v149, v152, 0x3f2aaada
	v_sub_f32_e32 v147, v146, v153
; __device__ __forceinline__ void ph_dt_tasks(Frame& F, int layer) {
;     ...
;             for (int q = 0; q < 4; ++q) { float* o = pDT + (size_t)(row0 + 4 * g + q) * 32 + r; const float x0 = a0[q] + b0, x1 = a1[q] + b1;
;                 o[0] = fmaxf(x0, 0.f) + log1pf(__expf(-fabsf(x0))); o[16] = fmaxf(x1, 0.f) + log1pf(__expf(-fabsf(x1))); }
	v_ldexp_f32 v153, v148, 1
	v_mul_f32_e32 v148, v148, v149
	v_mul_f32_e32 v148, v148, v152
	v_add_f32_e32 v149, v153, v148
	v_sub_f32_e32 v152, v149, v153
	v_ldexp_f32 v137, v137, 1
	v_sub_f32_e32 v148, v148, v152
	v_add_f32_e32 v137, v137, v148
	v_add_f32_e32 v148, v149, v137
	v_sub_f32_e32 v149, v148, v149
	v_sub_f32_e32 v137, v137, v149
	v_add_f32_e32 v149, v146, v148
	v_sub_f32_e32 v152, v149, v146
	v_sub_f32_e32 v153, v149, v152
	v_sub_f32_e32 v147, v154, v147
	v_sub_f32_e32 v146, v146, v153
	v_sub_f32_e32 v148, v148, v152
	v_add_f32_e32 v146, v148, v146
	v_add_f32_e32 v148, v147, v137
	v_sub_f32_e32 v152, v148, v147
	v_sub_f32_e32 v153, v148, v152
	v_sub_f32_e32 v147, v147, v153
	v_sub_f32_e32 v137, v137, v152
	v_add_f32_e32 v146, v148, v146
	v_add_f32_e32 v137, v137, v147
	v_add_f32_e32 v147, v149, v146
	v_sub_f32_e32 v148, v147, v149
	v_sub_f32_e32 v146, v146, v148
	v_add_f32_e32 v137, v137, v146
	v_add_f32_e32 v137, v147, v137
	v_cndmask_b32_e32 v137, v217, v137, vcc
	v_cmp_ngt_f32_e32 vcc, -1.0, v134
	s_nop 1
	v_cndmask_b32_e32 v137, v218, v137, vcc
	v_cmp_neq_f32_e32 vcc, -1.0, v134
	s_nop 1
	v_cndmask_b32_e32 v137, v219, v137, vcc
	v_cmp_lt_f32_e64 vcc, |v134|, s8
	s_nop 1
	v_cndmask_b32_e32 v134, v137, v134, vcc
	v_add_f32_e32 v132, v132, v134
	global_store_dword v[138:139], v132, off offset:64
	v_add_f32_e32 v132, v141, v133
	v_add_f32_e32 v134, v150, v135
	v_max_f32_e32 v135, 0, v132
	v_mul_f32_e64 v132, |v132|, s3
	v_exp_f32_e32 v138, v132
	v_ashrrev_i32_e32 v137, 31, v136
	v_lshlrev_b64 v[136:137], 7, v[136:137]
	v_lshl_add_u64 v[136:137], v[144:145], 0, v[136:137]
	v_add_f32_e32 v139, 1.0, v138
	v_add_f32_e32 v132, -1.0, v139
	v_sub_f32_e32 v133, v132, v139
	v_add_f32_e32 v133, 1.0, v133
	v_sub_f32_e32 v132, v138, v132
	v_add_f32_e32 v146, v132, v133
	v_frexp_mant_f32_e32 v132, v139
	v_cmp_gt_f32_e32 vcc, s4, v132
	v_cvt_f64_f32_e32 v[132:133], v139
	v_frexp_exp_i32_f64_e32 v132, v[132:133]
	v_subbrev_co_u32_e32 v132, vcc, 0, v132, vcc
	v_sub_u32_e32 v133, 0, v132
	v_ldexp_f32 v139, v139, v133
	v_ldexp_f32 v133, v146, v133
	v_add_f32_e32 v146, -1.0, v139
	v_add_f32_e32 v147, 1.0, v146
	v_sub_f32_e32 v147, v139, v147
	v_add_f32_e32 v147, v133, v147
	v_add_f32_e32 v148, v146, v147
	v_sub_f32_e32 v146, v148, v146
	v_sub_f32_e32 v146, v147, v146
	v_add_f32_e32 v147, 1.0, v139
	v_add_f32_e32 v149, -1.0, v147
	v_sub_f32_e32 v139, v139, v149
	v_add_f32_e32 v133, v133, v139
	v_add_f32_e32 v139, v147, v133
	v_sub_f32_e32 v147, v139, v147
	v_sub_f32_e32 v133, v133, v147
	v_rcp_f32_e32 v147, v139
	v_cvt_f32_i32_e32 v132, v132
	v_cmp_neq_f32_e32 vcc, s7, v138
	v_mul_f32_e32 v149, v148, v147
	v_mul_f32_e32 v152, v139, v149
	v_fma_f32 v153, v149, v139, -v152
	v_fmac_f32_e32 v153, v149, v133
	v_add_f32_e32 v154, v152, v153
	v_sub_f32_e32 v155, v148, v154
	v_sub_f32_e32 v148, v148, v155
	v_sub_f32_e32 v152, v154, v152
	v_sub_f32_e32 v148, v148, v154
	v_add_f32_e32 v146, v146, v148
	v_sub_f32_e32 v148, v152, v153
	v_add_f32_e32 v146, v148, v146
	v_add_f32_e32 v148, v155, v146
	v_mul_f32_e32 v152, v147, v148
	v_mul_f32_e32 v153, v139, v152
	v_fma_f32 v139, v152, v139, -v153
	v_fmac_f32_e32 v139, v152, v133
	v_sub_f32_e32 v133, v155, v148
	v_add_f32_e32 v133, v146, v133
	v_add_f32_e32 v146, v153, v139
	v_sub_f32_e32 v154, v148, v146
	v_sub_f32_e32 v148, v148, v154
	v_sub_f32_e32 v153, v146, v153
	v_sub_f32_e32 v146, v148, v146
	v_add_f32_e32 v133, v133, v146
	v_sub_f32_e32 v139, v153, v139
	v_add_f32_e32 v133, v139, v133
	v_add_f32_e32 v139, v149, v152
	v_add_f32_e32 v133, v154, v133
	v_sub_f32_e32 v146, v139, v149
	v_mul_f32_e32 v133, v147, v133
	v_sub_f32_e32 v146, v152, v146
	v_add_f32_e32 v133, v146, v133
	v_mul_f32_e32 v149, 0x3f317218, v132
	v_add_f32_e32 v146, v139, v133
	v_fma_f32 v152, v132, s5, -v149
	v_mul_f32_e32 v147, v146, v146
	v_fmac_f32_e32 v152, 0xb102e308, v132
	v_sub_f32_e32 v132, v146, v139
	v_fmamk_f32 v148, v147, 0x3e9b6dac, v215
	v_sub_f32_e32 v132, v133, v132
	v_add_f32_e32 v133, v149, v152
	v_fmaak_f32 v148, v147, v148, 0x3f2aaada
	v_sub_f32_e32 v139, v133, v149
	v_ldexp_f32 v149, v146, 1
	v_mul_f32_e32 v146, v146, v147
	v_mul_f32_e32 v146, v146, v148
	v_add_f32_e32 v147, v149, v146
	v_sub_f32_e32 v148, v147, v149
	v_ldexp_f32 v132, v132, 1
	v_sub_f32_e32 v146, v146, v148
	v_add_f32_e32 v132, v132, v146
	v_add_f32_e32 v146, v147, v132
	v_sub_f32_e32 v147, v146, v147
	v_sub_f32_e32 v132, v132, v147
	v_add_f32_e32 v147, v133, v146
	v_sub_f32_e32 v148, v147, v133
	v_sub_f32_e32 v149, v147, v148
	v_sub_f32_e32 v139, v152, v139
	v_sub_f32_e32 v133, v133, v149
	v_sub_f32_e32 v146, v146, v148
	v_add_f32_e32 v133, v146, v133
; __device__ __forceinline__ void ph_dt_tasks(Frame& F, int layer) {
;     ...
;             for (int q = 0; q < 4; ++q) { float* o = pDT + (size_t)(row0 + 4 * g + q) * 32 + r; const float x0 = a0[q] + b0, x1 = a1[q] + b1;
;                 o[0] = fmaxf(x0, 0.f) + log1pf(__expf(-fabsf(x0))); o[16] = fmaxf(x1, 0.f) + log1pf(__expf(-fabsf(x1))); }
	v_add_f32_e32 v146, v139, v132
	v_sub_f32_e32 v148, v146, v139
	v_sub_f32_e32 v149, v146, v148
	v_sub_f32_e32 v139, v139, v149
	v_sub_f32_e32 v132, v132, v148
	v_add_f32_e32 v133, v146, v133
	v_add_f32_e32 v132, v132, v139
	v_add_f32_e32 v139, v147, v133
	v_sub_f32_e32 v146, v139, v147
	v_sub_f32_e32 v133, v133, v146
	v_add_f32_e32 v132, v132, v133
	v_add_f32_e32 v132, v139, v132
	v_cndmask_b32_e32 v132, v217, v132, vcc
	v_cmp_ngt_f32_e32 vcc, -1.0, v138
	s_nop 1
	v_cndmask_b32_e32 v132, v218, v132, vcc
	v_cmp_neq_f32_e32 vcc, -1.0, v138
	s_nop 1
	v_cndmask_b32_e32 v132, v219, v132, vcc
	v_cmp_lt_f32_e64 vcc, |v138|, s8
	s_nop 1
	v_cndmask_b32_e32 v132, v132, v138, vcc
	v_add_f32_e32 v132, v135, v132
	global_store_dword v[136:137], v132, off
	v_mul_f32_e64 v132, |v134|, s3
	v_max_f32_e32 v135, 0, v134
	v_exp_f32_e32 v134, v132
	s_nop 0
	v_add_f32_e32 v138, 1.0, v134
	v_add_f32_e32 v132, -1.0, v138
	v_sub_f32_e32 v133, v132, v138
	v_add_f32_e32 v133, 1.0, v133
	v_sub_f32_e32 v132, v134, v132
	v_add_f32_e32 v139, v132, v133
	v_frexp_mant_f32_e32 v132, v138
	v_cmp_gt_f32_e32 vcc, s4, v132
	v_cvt_f64_f32_e32 v[132:133], v138
	v_frexp_exp_i32_f64_e32 v132, v[132:133]
	v_subbrev_co_u32_e32 v132, vcc, 0, v132, vcc
	v_sub_u32_e32 v133, 0, v132
	v_ldexp_f32 v138, v138, v133
	v_ldexp_f32 v133, v139, v133
	v_add_f32_e32 v139, -1.0, v138
	v_add_f32_e32 v146, 1.0, v139
	v_sub_f32_e32 v146, v138, v146
	v_add_f32_e32 v146, v133, v146
	v_add_f32_e32 v147, v139, v146
	v_sub_f32_e32 v139, v147, v139
	v_sub_f32_e32 v139, v146, v139
	v_add_f32_e32 v146, 1.0, v138
	v_add_f32_e32 v148, -1.0, v146
	v_sub_f32_e32 v138, v138, v148
	v_add_f32_e32 v133, v133, v138
	v_add_f32_e32 v138, v146, v133
	v_sub_f32_e32 v146, v138, v146
	v_sub_f32_e32 v133, v133, v146
	v_rcp_f32_e32 v146, v138
	v_cvt_f32_i32_e32 v132, v132
	v_cmp_neq_f32_e32 vcc, s7, v134
	v_mul_f32_e32 v148, v147, v146
	v_mul_f32_e32 v149, v138, v148
	v_fma_f32 v152, v148, v138, -v149
	v_fmac_f32_e32 v152, v148, v133
	v_add_f32_e32 v153, v149, v152
	v_sub_f32_e32 v154, v147, v153
	v_sub_f32_e32 v147, v147, v154
	v_sub_f32_e32 v149, v153, v149
	v_sub_f32_e32 v147, v147, v153
	v_add_f32_e32 v139, v139, v147
	v_sub_f32_e32 v147, v149, v152
	v_add_f32_e32 v139, v147, v139
	v_add_f32_e32 v147, v154, v139
	v_mul_f32_e32 v149, v146, v147
	v_mul_f32_e32 v152, v138, v149
	v_fma_f32 v138, v149, v138, -v152
	v_fmac_f32_e32 v138, v149, v133
	v_sub_f32_e32 v133, v154, v147
	v_add_f32_e32 v133, v139, v133
	v_add_f32_e32 v139, v152, v138
	v_sub_f32_e32 v153, v147, v139
	v_sub_f32_e32 v147, v147, v153
	v_sub_f32_e32 v152, v139, v152
	v_sub_f32_e32 v139, v147, v139
	v_add_f32_e32 v133, v133, v139
	v_sub_f32_e32 v138, v152, v138
	v_add_f32_e32 v133, v138, v133
	v_add_f32_e32 v138, v148, v149
	v_add_f32_e32 v133, v153, v133
	v_sub_f32_e32 v139, v138, v148
	v_mul_f32_e32 v133, v146, v133
	v_sub_f32_e32 v139, v149, v139
	v_add_f32_e32 v133, v139, v133
	v_mul_f32_e32 v148, 0x3f317218, v132
	v_add_f32_e32 v139, v138, v133
	v_fma_f32 v149, v132, s5, -v148
	v_mul_f32_e32 v146, v139, v139
	v_fmac_f32_e32 v149, 0xb102e308, v132
	v_sub_f32_e32 v132, v139, v138
	v_fmamk_f32 v147, v146, 0x3e9b6dac, v215
	v_sub_f32_e32 v132, v133, v132
	v_add_f32_e32 v133, v148, v149
	v_fmaak_f32 v147, v146, v147, 0x3f2aaada
	v_sub_f32_e32 v138, v133, v148
	v_ldexp_f32 v148, v139, 1
	v_mul_f32_e32 v139, v139, v146
	v_mul_f32_e32 v139, v139, v147
	v_add_f32_e32 v146, v148, v139
	v_sub_f32_e32 v147, v146, v148
	v_ldexp_f32 v132, v132, 1
	v_sub_f32_e32 v139, v139, v147
	v_add_f32_e32 v132, v132, v139
	v_add_f32_e32 v139, v146, v132
	v_sub_f32_e32 v146, v139, v146
	v_sub_f32_e32 v132, v132, v146
	v_add_f32_e32 v146, v133, v139
	v_sub_f32_e32 v147, v146, v133
	v_sub_f32_e32 v148, v146, v147
	v_sub_f32_e32 v138, v149, v138
	v_sub_f32_e32 v133, v133, v148
	v_sub_f32_e32 v139, v139, v147
	v_add_f32_e32 v133, v139, v133
	v_add_f32_e32 v139, v138, v132
	v_sub_f32_e32 v147, v139, v138
	v_sub_f32_e32 v148, v139, v147
	v_sub_f32_e32 v138, v138, v148
	v_sub_f32_e32 v132, v132, v147
	v_add_f32_e32 v133, v139, v133
	v_add_f32_e32 v132, v132, v138
	v_add_f32_e32 v138, v146, v133
	v_sub_f32_e32 v139, v138, v146
	v_sub_f32_e32 v133, v133, v139
	v_add_f32_e32 v132, v132, v133
	v_add_f32_e32 v132, v138, v132
	v_cndmask_b32_e32 v132, v217, v132, vcc
	v_cmp_ngt_f32_e32 vcc, -1.0, v134
	s_nop 1
	v_cndmask_b32_e32 v132, v218, v132, vcc
	v_cmp_neq_f32_e32 vcc, -1.0, v134
	s_nop 1
	v_cndmask_b32_e32 v132, v219, v132, vcc
	v_cmp_lt_f32_e64 vcc, |v134|, s8
	s_nop 1
	v_cndmask_b32_e32 v132, v132, v134, vcc
	v_add_f32_e32 v132, v135, v132
	global_store_dword v[136:137], v132, off offset:64
	s_branch .LBB0_769

; #define ROWS_UNPK(w, lo, hi) do { lo = (f32x4){bflo((w)[0]), bfhi((w)[0]), bflo((w)[1]), bfhi((w)[1])}; hi = (f32x4){bflo((w)[2]), bfhi((w)[2]), bflo((w)[3]), bfhi((w)[3])}; } while (0)
; template <bool XINB, bool XOUTB> __device__ __forceinline__ void ph_rows(Frame& F, int nrows, const void* xin_l, const void* xin_c, void* xout_l, void* xout_c, const bf16* Y, const bf16* Ypart, ...
;     ...
;             if (!lat && Ypart) {
; #pragma unroll
;                 for (int jj = 0; jj < 4; ++jj) { f32x4 a0 = {0.f, 0.f, 0.f, 0.f}, a1 = a0;
; #pragma unroll
;                     for (int sp = 0; sp < KSPLIT; ++sp) { const v4u yw = *(const v4u*)(Ypart + ((size_t)sp * MC + (row - ML)) * D + ROWS_COL(jj)); f32x4 p0, p1; ROWS_UNPK(yw, p0, p1); a0 += p0; a1 += p1; }
;                     y[2 * jj] = a0; y[2 * jj + 1] = a1; }
.LBB0_1364:
	s_andn2_b64 vcc, exec, s[18:19]
	s_cbranch_vccnz .LBB0_1366
	s_add_i32 s92, s38, 0xffffc000
	s_lshl_b64 s[18:19], s[92:93], 12
	v_lshl_add_u64 v[66:67], v[94:95], 0, s[18:19]
	s_mov_b32 s18, 0x400000
	v_add_co_u32_e32 v64, vcc, s18, v66
	s_nop 1
	v_addc_co_u32_e32 v65, vcc, 0, v67, vcc
	s_mov_b32 s18, 0x800000
	v_add_co_u32_e32 v62, vcc, s18, v66
	s_nop 1
	v_addc_co_u32_e32 v63, vcc, 0, v67, vcc
	s_mov_b32 s18, 0xc00000
	v_add_co_u32_e32 v60, vcc, s18, v66
	s_nop 1
	v_addc_co_u32_e32 v61, vcc, 0, v67, vcc
	global_load_dwordx4 v[144:147], v[66:67], off
	global_load_dwordx4 v[148:151], v[64:65], off
	global_load_dwordx4 v[152:155], v[62:63], off
	global_load_dwordx4 v[156:159], v[60:61], off
	global_load_dwordx4 v[160:163], v[66:67], off offset:1024
	global_load_dwordx4 v[164:167], v[64:65], off offset:1024
	global_load_dwordx4 v[172:175], v[62:63], off offset:1024
	global_load_dwordx4 v[176:179], v[60:61], off offset:1024
	global_load_dwordx4 v[180:183], v[66:67], off offset:2048
	global_load_dwordx4 v[184:187], v[64:65], off offset:2048
	global_load_dwordx4 v[188:191], v[62:63], off offset:2048
	global_load_dwordx4 v[192:195], v[60:61], off offset:2048
	global_load_dwordx4 v[196:199], v[66:67], off offset:3072
	global_load_dwordx4 v[200:203], v[64:65], off offset:3072
	global_load_dwordx4 v[204:207], v[62:63], off offset:3072
	global_load_dwordx4 v[208:211], v[60:61], off offset:3072
	s_waitcnt vmcnt(15)
	v_mov_b32_e32 v36, v144
	v_mov_b32_e32 v37, v145
	v_mov_b32_e32 v38, v146
	v_mov_b32_e32 v39, v147
	v_lshlrev_b32_e32 v40, 16, v36
	v_and_b32_e32 v41, 0xffff0000, v36
	v_lshlrev_b32_e32 v36, 16, v37
	v_and_b32_e32 v37, 0xffff0000, v37
	v_lshlrev_b32_e32 v42, 16, v38
	v_and_b32_e32 v43, 0xffff0000, v38
	v_lshlrev_b32_e32 v38, 16, v39
	v_and_b32_e32 v39, 0xffff0000, v39
	v_pk_add_f32 v[44:45], v[36:37], 0 op_sel_hi:[1,0]
	v_pk_add_f32 v[46:47], v[38:39], 0 op_sel_hi:[1,0]
	v_pk_add_f32 v[40:41], v[40:41], 0 op_sel_hi:[1,0]
	v_pk_add_f32 v[42:43], v[42:43], 0 op_sel_hi:[1,0]
	s_waitcnt vmcnt(14)
	v_mov_b32_e32 v36, v148
	v_mov_b32_e32 v37, v149
	v_mov_b32_e32 v38, v150
	v_mov_b32_e32 v39, v151
	v_lshlrev_b32_e32 v48, 16, v36
	v_and_b32_e32 v49, 0xffff0000, v36
	v_lshlrev_b32_e32 v36, 16, v37
	v_and_b32_e32 v37, 0xffff0000, v37
	v_lshlrev_b32_e32 v50, 16, v38
	v_and_b32_e32 v51, 0xffff0000, v38
	v_lshlrev_b32_e32 v38, 16, v39
	v_and_b32_e32 v39, 0xffff0000, v39
	v_pk_add_f32 v[44:45], v[44:45], v[36:37]
	v_pk_add_f32 v[46:47], v[46:47], v[38:39]
	v_pk_add_f32 v[40:41], v[40:41], v[48:49]
	v_pk_add_f32 v[42:43], v[42:43], v[50:51]
	s_waitcnt vmcnt(13)
	v_mov_b32_e32 v36, v152
	v_mov_b32_e32 v37, v153
	v_mov_b32_e32 v38, v154
	v_mov_b32_e32 v39, v155
	v_lshlrev_b32_e32 v48, 16, v36
	v_and_b32_e32 v49, 0xffff0000, v36
	v_lshlrev_b32_e32 v36, 16, v37
	v_and_b32_e32 v37, 0xffff0000, v37
	v_lshlrev_b32_e32 v50, 16, v38
	v_and_b32_e32 v51, 0xffff0000, v38
	v_lshlrev_b32_e32 v38, 16, v39
	v_and_b32_e32 v39, 0xffff0000, v39
	v_pk_add_f32 v[40:41], v[40:41], v[48:49]
	v_pk_add_f32 v[44:45], v[44:45], v[36:37]
	v_pk_add_f32 v[48:49], v[42:43], v[50:51]
	v_pk_add_f32 v[42:43], v[46:47], v[38:39]
	s_waitcnt vmcnt(12)
	v_mov_b32_e32 v36, v156
	v_mov_b32_e32 v37, v157
	v_mov_b32_e32 v38, v158
	v_mov_b32_e32 v39, v159
	v_lshlrev_b32_e32 v46, 16, v36
	v_and_b32_e32 v47, 0xffff0000, v36
	v_lshlrev_b32_e32 v36, 16, v37
	v_and_b32_e32 v37, 0xffff0000, v37
	v_lshlrev_b32_e32 v50, 16, v38
	v_and_b32_e32 v51, 0xffff0000, v38
	v_lshlrev_b32_e32 v52, 16, v39
	v_and_b32_e32 v53, 0xffff0000, v39
	v_pk_add_f32 v[38:39], v[44:45], v[36:37]
	v_pk_add_f32 v[36:37], v[40:41], v[46:47]
	v_pk_add_f32 v[40:41], v[48:49], v[50:51]
	v_pk_add_f32 v[42:43], v[42:43], v[52:53]
	s_waitcnt vmcnt(11)
	v_mov_b32_e32 v44, v160
	v_mov_b32_e32 v45, v161
	v_mov_b32_e32 v46, v162
	v_mov_b32_e32 v47, v163
	v_lshlrev_b32_e32 v48, 16, v44
	v_and_b32_e32 v49, 0xffff0000, v44
	v_lshlrev_b32_e32 v44, 16, v45
	v_and_b32_e32 v45, 0xffff0000, v45
	v_lshlrev_b32_e32 v50, 16, v46
	v_and_b32_e32 v51, 0xffff0000, v46
	v_lshlrev_b32_e32 v46, 16, v47
	v_and_b32_e32 v47, 0xffff0000, v47
	v_pk_add_f32 v[52:53], v[44:45], 0 op_sel_hi:[1,0]
	v_pk_add_f32 v[54:55], v[46:47], 0 op_sel_hi:[1,0]
	v_pk_add_f32 v[48:49], v[48:49], 0 op_sel_hi:[1,0]
	v_pk_add_f32 v[50:51], v[50:51], 0 op_sel_hi:[1,0]
	s_waitcnt vmcnt(10)
	v_mov_b32_e32 v44, v164
	v_mov_b32_e32 v45, v165
	v_mov_b32_e32 v46, v166
	v_mov_b32_e32 v47, v167
	v_lshlrev_b32_e32 v56, 16, v44
	v_and_b32_e32 v57, 0xffff0000, v44
	v_lshlrev_b32_e32 v44, 16, v45
	v_and_b32_e32 v45, 0xffff0000, v45
	v_lshlrev_b32_e32 v58, 16, v46
	v_and_b32_e32 v59, 0xffff0000, v46
	v_lshlrev_b32_e32 v46, 16, v47
	v_and_b32_e32 v47, 0xffff0000, v47
	v_pk_add_f32 v[52:53], v[52:53], v[44:45]
	v_pk_add_f32 v[54:55], v[54:55], v[46:47]
	v_pk_add_f32 v[48:49], v[48:49], v[56:57]
	v_pk_add_f32 v[50:51], v[50:51], v[58:59]
	s_waitcnt vmcnt(9)
	v_mov_b32_e32 v44, v172
	v_mov_b32_e32 v45, v173
	v_mov_b32_e32 v46, v174
	v_mov_b32_e32 v47, v175
	v_lshlrev_b32_e32 v56, 16, v44
	v_and_b32_e32 v57, 0xffff0000, v44
	v_lshlrev_b32_e32 v44, 16, v45
	v_and_b32_e32 v45, 0xffff0000, v45
	v_lshlrev_b32_e32 v58, 16, v46
	v_and_b32_e32 v59, 0xffff0000, v46
	v_lshlrev_b32_e32 v46, 16, v47
	v_and_b32_e32 v47, 0xffff0000, v47
	v_pk_add_f32 v[48:49], v[48:49], v[56:57]
	v_pk_add_f32 v[52:53], v[52:53], v[44:45]
	v_pk_add_f32 v[56:57], v[50:51], v[58:59]
	v_pk_add_f32 v[50:51], v[54:55], v[46:47]
	s_waitcnt vmcnt(8)
; #define ROWS_UNPK(w, lo, hi) do { lo = (f32x4){bflo((w)[0]), bfhi((w)[0]), bflo((w)[1]), bfhi((w)[1])}; hi = (f32x4){bflo((w)[2]), bfhi((w)[2]), bflo((w)[3]), bfhi((w)[3])}; } while (0)
; template <bool XINB, bool XOUTB> __device__ __forceinline__ void ph_rows(Frame& F, int nrows, const void* xin_l, const void* xin_c, void* xout_l, void* xout_c, const bf16* Y, const bf16* Ypart, ...
;     ...
;             if (!lat && Ypart) {
; #pragma unroll
;                 for (int jj = 0; jj < 4; ++jj) { f32x4 a0 = {0.f, 0.f, 0.f, 0.f}, a1 = a0;
; #pragma unroll
;                     for (int sp = 0; sp < KSPLIT; ++sp) { const v4u yw = *(const v4u*)(Ypart + ((size_t)sp * MC + (row - ML)) * D + ROWS_COL(jj)); f32x4 p0, p1; ROWS_UNPK(yw, p0, p1); a0 += p0; a1 += p1; }
;                     y[2 * jj] = a0; y[2 * jj + 1] = a1; }
	v_mov_b32_e32 v44, v176
	v_mov_b32_e32 v45, v177
	v_mov_b32_e32 v46, v178
	v_mov_b32_e32 v47, v179
	v_lshlrev_b32_e32 v54, 16, v44
	v_and_b32_e32 v55, 0xffff0000, v44
	v_lshlrev_b32_e32 v44, 16, v45
	v_and_b32_e32 v45, 0xffff0000, v45
	v_lshlrev_b32_e32 v58, 16, v46
	v_and_b32_e32 v59, 0xffff0000, v46
	v_lshlrev_b32_e32 v68, 16, v47
	v_and_b32_e32 v69, 0xffff0000, v47
	v_pk_add_f32 v[46:47], v[52:53], v[44:45]
	v_pk_add_f32 v[44:45], v[48:49], v[54:55]
	v_pk_add_f32 v[48:49], v[56:57], v[58:59]
	v_pk_add_f32 v[50:51], v[50:51], v[68:69]
	s_waitcnt vmcnt(7)
	v_mov_b32_e32 v52, v180
	v_mov_b32_e32 v53, v181
	v_mov_b32_e32 v54, v182
	v_mov_b32_e32 v55, v183
	v_lshlrev_b32_e32 v56, 16, v52
	v_and_b32_e32 v57, 0xffff0000, v52
	v_lshlrev_b32_e32 v52, 16, v53
	v_and_b32_e32 v53, 0xffff0000, v53
	v_lshlrev_b32_e32 v58, 16, v54
	v_and_b32_e32 v59, 0xffff0000, v54
	v_lshlrev_b32_e32 v54, 16, v55
	v_and_b32_e32 v55, 0xffff0000, v55
	v_pk_add_f32 v[68:69], v[52:53], 0 op_sel_hi:[1,0]
	v_pk_add_f32 v[70:71], v[54:55], 0 op_sel_hi:[1,0]
	v_pk_add_f32 v[56:57], v[56:57], 0 op_sel_hi:[1,0]
	v_pk_add_f32 v[58:59], v[58:59], 0 op_sel_hi:[1,0]
	s_waitcnt vmcnt(6)
	v_mov_b32_e32 v52, v184
	v_mov_b32_e32 v53, v185
	v_mov_b32_e32 v54, v186
	v_mov_b32_e32 v55, v187
	v_lshlrev_b32_e32 v72, 16, v52
	v_and_b32_e32 v73, 0xffff0000, v52
	v_lshlrev_b32_e32 v52, 16, v53
	v_and_b32_e32 v53, 0xffff0000, v53
	v_lshlrev_b32_e32 v74, 16, v54
	v_and_b32_e32 v75, 0xffff0000, v54
	v_lshlrev_b32_e32 v54, 16, v55
	v_and_b32_e32 v55, 0xffff0000, v55
	v_pk_add_f32 v[68:69], v[68:69], v[52:53]
	v_pk_add_f32 v[70:71], v[70:71], v[54:55]
	v_pk_add_f32 v[56:57], v[56:57], v[72:73]
	v_pk_add_f32 v[58:59], v[58:59], v[74:75]
	s_waitcnt vmcnt(5)
	v_mov_b32_e32 v52, v188
	v_mov_b32_e32 v53, v189
	v_mov_b32_e32 v54, v190
	v_mov_b32_e32 v55, v191
	v_lshlrev_b32_e32 v72, 16, v52
	v_and_b32_e32 v73, 0xffff0000, v52
	v_lshlrev_b32_e32 v52, 16, v53
	v_and_b32_e32 v53, 0xffff0000, v53
	v_lshlrev_b32_e32 v74, 16, v54
	v_and_b32_e32 v75, 0xffff0000, v54
	v_lshlrev_b32_e32 v54, 16, v55
	v_and_b32_e32 v55, 0xffff0000, v55
	v_pk_add_f32 v[56:57], v[56:57], v[72:73]
	v_pk_add_f32 v[68:69], v[68:69], v[52:53]
	v_pk_add_f32 v[72:73], v[58:59], v[74:75]
	v_pk_add_f32 v[58:59], v[70:71], v[54:55]
	s_waitcnt vmcnt(4)
	v_mov_b32_e32 v52, v192
	v_mov_b32_e32 v53, v193
	v_mov_b32_e32 v54, v194
	v_mov_b32_e32 v55, v195
	v_lshlrev_b32_e32 v70, 16, v52
	v_and_b32_e32 v71, 0xffff0000, v52
	v_lshlrev_b32_e32 v52, 16, v53
	v_and_b32_e32 v53, 0xffff0000, v53
	v_lshlrev_b32_e32 v74, 16, v54
	v_and_b32_e32 v75, 0xffff0000, v54
	v_lshlrev_b32_e32 v76, 16, v55
	v_and_b32_e32 v77, 0xffff0000, v55
	v_pk_add_f32 v[54:55], v[68:69], v[52:53]
	v_pk_add_f32 v[52:53], v[56:57], v[70:71]
	v_pk_add_f32 v[56:57], v[72:73], v[74:75]
	v_pk_add_f32 v[58:59], v[58:59], v[76:77]
	s_waitcnt vmcnt(3)
	v_mov_b32_e32 v66, v196
	v_mov_b32_e32 v67, v197
	v_mov_b32_e32 v68, v198
	v_mov_b32_e32 v69, v199
	v_lshlrev_b32_e32 v70, 16, v66
	v_and_b32_e32 v71, 0xffff0000, v66
	v_lshlrev_b32_e32 v66, 16, v67
	v_and_b32_e32 v67, 0xffff0000, v67
	v_pk_add_f32 v[74:75], v[66:67], 0 op_sel_hi:[1,0]
	v_lshlrev_b32_e32 v72, 16, v68
	v_and_b32_e32 v73, 0xffff0000, v68
	v_lshlrev_b32_e32 v68, 16, v69
	v_and_b32_e32 v69, 0xffff0000, v69
	v_pk_add_f32 v[70:71], v[70:71], 0 op_sel_hi:[1,0]
	v_pk_add_f32 v[68:69], v[68:69], 0 op_sel_hi:[1,0]
	v_pk_add_f32 v[72:73], v[72:73], 0 op_sel_hi:[1,0]
	s_waitcnt vmcnt(2)
	v_mov_b32_e32 v64, v200
	v_mov_b32_e32 v65, v201
	v_mov_b32_e32 v66, v202
	v_mov_b32_e32 v67, v203
	v_lshlrev_b32_e32 v76, 16, v64
	v_and_b32_e32 v77, 0xffff0000, v64
	v_lshlrev_b32_e32 v64, 16, v65
	v_and_b32_e32 v65, 0xffff0000, v65
	v_pk_add_f32 v[74:75], v[74:75], v[64:65]
	v_lshlrev_b32_e32 v78, 16, v66
	v_and_b32_e32 v79, 0xffff0000, v66
	v_lshlrev_b32_e32 v66, 16, v67
	v_and_b32_e32 v67, 0xffff0000, v67
	v_pk_add_f32 v[70:71], v[70:71], v[76:77]
	v_pk_add_f32 v[66:67], v[68:69], v[66:67]
	v_pk_add_f32 v[72:73], v[72:73], v[78:79]
	s_waitcnt vmcnt(1)
	v_mov_b32_e32 v62, v204
	v_mov_b32_e32 v63, v205
	v_mov_b32_e32 v64, v206
	v_mov_b32_e32 v65, v207
	v_lshlrev_b32_e32 v68, 16, v62
	v_and_b32_e32 v69, 0xffff0000, v62
	v_lshlrev_b32_e32 v62, 16, v63
	v_and_b32_e32 v63, 0xffff0000, v63
	v_pk_add_f32 v[68:69], v[70:71], v[68:69]
	v_pk_add_f32 v[70:71], v[74:75], v[62:63]
	v_lshlrev_b32_e32 v76, 16, v64
	v_and_b32_e32 v77, 0xffff0000, v64
	v_lshlrev_b32_e32 v78, 16, v65
	v_and_b32_e32 v79, 0xffff0000, v65
	v_pk_add_f32 v[64:65], v[72:73], v[76:77]
	v_pk_add_f32 v[66:67], v[66:67], v[78:79]
	s_waitcnt vmcnt(0)
	v_mov_b32_e32 v60, v208
	v_mov_b32_e32 v61, v209
	v_mov_b32_e32 v62, v210
	v_mov_b32_e32 v63, v211
	v_lshlrev_b32_e32 v72, 16, v60
	v_and_b32_e32 v73, 0xffff0000, v60
	v_lshlrev_b32_e32 v60, 16, v61
	v_and_b32_e32 v61, 0xffff0000, v61
	v_lshlrev_b32_e32 v74, 16, v62
	v_and_b32_e32 v75, 0xffff0000, v62
	v_lshlrev_b32_e32 v76, 16, v63
	v_and_b32_e32 v77, 0xffff0000, v63
	v_pk_add_f32 v[62:63], v[70:71], v[60:61]
	v_pk_add_f32 v[60:61], v[68:69], v[72:73]
	v_pk_add_f32 v[66:67], v[66:67], v[76:77]
	v_pk_add_f32 v[64:65], v[64:65], v[74:75]

; #define ROWS_UNPK(w, lo, hi) do { lo = (f32x4){bflo((w)[0]), bfhi((w)[0]), bflo((w)[1]), bfhi((w)[1])}; hi = (f32x4){bflo((w)[2]), bfhi((w)[2]), bflo((w)[3]), bfhi((w)[3])}; } while (0)
; template <bool XINB, bool XOUTB> __device__ __forceinline__ void ph_rows(Frame& F, int nrows, const void* xin_l, const void* xin_c, void* xout_l, void* xout_c, const bf16* Y, const bf16* Ypart, ...
;     ...
;             if (!lat && Ypart) {
; #pragma unroll
;                 for (int jj = 0; jj < 4; ++jj) { f32x4 a0 = {0.f, 0.f, 0.f, 0.f}, a1 = a0;
; #pragma unroll
;                     for (int sp = 0; sp < KSPLIT; ++sp) { const v4u yw = *(const v4u*)(Ypart + ((size_t)sp * MC + (row - ML)) * D + ROWS_COL(jj)); f32x4 p0, p1; ROWS_UNPK(yw, p0, p1); a0 += p0; a1 += p1; }
;                     y[2 * jj] = a0; y[2 * jj + 1] = a1; }
.LBB0_1741:
	s_andn2_b64 vcc, exec, s[18:19]
	s_cbranch_vccnz .LBB0_1743
	s_add_i32 s92, s37, 0xffffc000
	s_lshl_b64 s[18:19], s[92:93], 12
	v_lshl_add_u64 v[66:67], v[94:95], 0, s[18:19]
	s_mov_b32 s18, 0x400000
	v_add_co_u32_e32 v64, vcc, s18, v66
	s_nop 1
	v_addc_co_u32_e32 v65, vcc, 0, v67, vcc
	s_mov_b32 s18, 0x800000
	v_add_co_u32_e32 v62, vcc, s18, v66
	s_nop 1
	v_addc_co_u32_e32 v63, vcc, 0, v67, vcc
	s_mov_b32 s18, 0xc00000
	v_add_co_u32_e32 v60, vcc, s18, v66
	s_nop 1
	v_addc_co_u32_e32 v61, vcc, 0, v67, vcc
	global_load_dwordx4 v[144:147], v[66:67], off
	global_load_dwordx4 v[148:151], v[64:65], off
	global_load_dwordx4 v[152:155], v[62:63], off
	global_load_dwordx4 v[156:159], v[60:61], off
	global_load_dwordx4 v[160:163], v[66:67], off offset:1024
	global_load_dwordx4 v[164:167], v[64:65], off offset:1024
	global_load_dwordx4 v[172:175], v[62:63], off offset:1024
	global_load_dwordx4 v[176:179], v[60:61], off offset:1024
	global_load_dwordx4 v[180:183], v[66:67], off offset:2048
	global_load_dwordx4 v[184:187], v[64:65], off offset:2048
	global_load_dwordx4 v[188:191], v[62:63], off offset:2048
	global_load_dwordx4 v[192:195], v[60:61], off offset:2048
	global_load_dwordx4 v[196:199], v[66:67], off offset:3072
	global_load_dwordx4 v[200:203], v[64:65], off offset:3072
	global_load_dwordx4 v[204:207], v[62:63], off offset:3072
	global_load_dwordx4 v[208:211], v[60:61], off offset:3072
	s_waitcnt vmcnt(15)
	v_mov_b32_e32 v36, v144
	v_mov_b32_e32 v37, v145
	v_mov_b32_e32 v38, v146
	v_mov_b32_e32 v39, v147
	v_lshlrev_b32_e32 v40, 16, v36
	v_and_b32_e32 v41, 0xffff0000, v36
	v_lshlrev_b32_e32 v36, 16, v37
	v_and_b32_e32 v37, 0xffff0000, v37
	v_lshlrev_b32_e32 v42, 16, v38
	v_and_b32_e32 v43, 0xffff0000, v38
	v_lshlrev_b32_e32 v38, 16, v39
	v_and_b32_e32 v39, 0xffff0000, v39
	v_pk_add_f32 v[44:45], v[36:37], 0 op_sel_hi:[1,0]
	v_pk_add_f32 v[46:47], v[38:39], 0 op_sel_hi:[1,0]
	v_pk_add_f32 v[40:41], v[40:41], 0 op_sel_hi:[1,0]
	v_pk_add_f32 v[42:43], v[42:43], 0 op_sel_hi:[1,0]
	s_waitcnt vmcnt(14)
	v_mov_b32_e32 v36, v148
	v_mov_b32_e32 v37, v149
	v_mov_b32_e32 v38, v150
	v_mov_b32_e32 v39, v151
	v_lshlrev_b32_e32 v48, 16, v36
	v_and_b32_e32 v49, 0xffff0000, v36
	v_lshlrev_b32_e32 v36, 16, v37
	v_and_b32_e32 v37, 0xffff0000, v37
	v_lshlrev_b32_e32 v50, 16, v38
	v_and_b32_e32 v51, 0xffff0000, v38
	v_lshlrev_b32_e32 v38, 16, v39
	v_and_b32_e32 v39, 0xffff0000, v39
	v_pk_add_f32 v[44:45], v[44:45], v[36:37]
	v_pk_add_f32 v[46:47], v[46:47], v[38:39]
	v_pk_add_f32 v[40:41], v[40:41], v[48:49]
	v_pk_add_f32 v[42:43], v[42:43], v[50:51]
	s_waitcnt vmcnt(13)
	v_mov_b32_e32 v36, v152
	v_mov_b32_e32 v37, v153
	v_mov_b32_e32 v38, v154
	v_mov_b32_e32 v39, v155
	v_lshlrev_b32_e32 v48, 16, v36
	v_and_b32_e32 v49, 0xffff0000, v36
	v_lshlrev_b32_e32 v36, 16, v37
	v_and_b32_e32 v37, 0xffff0000, v37
	v_lshlrev_b32_e32 v50, 16, v38
	v_and_b32_e32 v51, 0xffff0000, v38
	v_lshlrev_b32_e32 v38, 16, v39
	v_and_b32_e32 v39, 0xffff0000, v39
	v_pk_add_f32 v[40:41], v[40:41], v[48:49]
	v_pk_add_f32 v[44:45], v[44:45], v[36:37]
	v_pk_add_f32 v[48:49], v[42:43], v[50:51]
	v_pk_add_f32 v[42:43], v[46:47], v[38:39]
	s_waitcnt vmcnt(12)
	v_mov_b32_e32 v36, v156
	v_mov_b32_e32 v37, v157
	v_mov_b32_e32 v38, v158
	v_mov_b32_e32 v39, v159
	v_lshlrev_b32_e32 v46, 16, v36
	v_and_b32_e32 v47, 0xffff0000, v36
	v_lshlrev_b32_e32 v36, 16, v37
	v_and_b32_e32 v37, 0xffff0000, v37
	v_lshlrev_b32_e32 v50, 16, v38
	v_and_b32_e32 v51, 0xffff0000, v38
	v_lshlrev_b32_e32 v52, 16, v39
	v_and_b32_e32 v53, 0xffff0000, v39
	v_pk_add_f32 v[38:39], v[44:45], v[36:37]
	v_pk_add_f32 v[36:37], v[40:41], v[46:47]
	v_pk_add_f32 v[40:41], v[48:49], v[50:51]
	v_pk_add_f32 v[42:43], v[42:43], v[52:53]
	s_waitcnt vmcnt(11)
	v_mov_b32_e32 v44, v160
	v_mov_b32_e32 v45, v161
	v_mov_b32_e32 v46, v162
	v_mov_b32_e32 v47, v163
	v_lshlrev_b32_e32 v48, 16, v44
	v_and_b32_e32 v49, 0xffff0000, v44
	v_lshlrev_b32_e32 v44, 16, v45
	v_and_b32_e32 v45, 0xffff0000, v45
	v_lshlrev_b32_e32 v50, 16, v46
	v_and_b32_e32 v51, 0xffff0000, v46
	v_lshlrev_b32_e32 v46, 16, v47
	v_and_b32_e32 v47, 0xffff0000, v47
	v_pk_add_f32 v[52:53], v[44:45], 0 op_sel_hi:[1,0]
	v_pk_add_f32 v[54:55], v[46:47], 0 op_sel_hi:[1,0]
	v_pk_add_f32 v[48:49], v[48:49], 0 op_sel_hi:[1,0]
	v_pk_add_f32 v[50:51], v[50:51], 0 op_sel_hi:[1,0]
	s_waitcnt vmcnt(10)
	v_mov_b32_e32 v44, v164
	v_mov_b32_e32 v45, v165
	v_mov_b32_e32 v46, v166
	v_mov_b32_e32 v47, v167
	v_lshlrev_b32_e32 v56, 16, v44
	v_and_b32_e32 v57, 0xffff0000, v44
	v_lshlrev_b32_e32 v44, 16, v45
	v_and_b32_e32 v45, 0xffff0000, v45
	v_lshlrev_b32_e32 v58, 16, v46
	v_and_b32_e32 v59, 0xffff0000, v46
	v_lshlrev_b32_e32 v46, 16, v47
	v_and_b32_e32 v47, 0xffff0000, v47
	v_pk_add_f32 v[52:53], v[52:53], v[44:45]
	v_pk_add_f32 v[54:55], v[54:55], v[46:47]
	v_pk_add_f32 v[48:49], v[48:49], v[56:57]
	v_pk_add_f32 v[50:51], v[50:51], v[58:59]
	s_waitcnt vmcnt(9)
	v_mov_b32_e32 v44, v172
	v_mov_b32_e32 v45, v173
	v_mov_b32_e32 v46, v174
	v_mov_b32_e32 v47, v175
	v_lshlrev_b32_e32 v56, 16, v44
	v_and_b32_e32 v57, 0xffff0000, v44
	v_lshlrev_b32_e32 v44, 16, v45
	v_and_b32_e32 v45, 0xffff0000, v45
	v_lshlrev_b32_e32 v58, 16, v46
	v_and_b32_e32 v59, 0xffff0000, v46
	v_lshlrev_b32_e32 v46, 16, v47
	v_and_b32_e32 v47, 0xffff0000, v47
	v_pk_add_f32 v[48:49], v[48:49], v[56:57]
	v_pk_add_f32 v[52:53], v[52:53], v[44:45]
	v_pk_add_f32 v[56:57], v[50:51], v[58:59]
	v_pk_add_f32 v[50:51], v[54:55], v[46:47]
	s_waitcnt vmcnt(8)
; #define ROWS_UNPK(w, lo, hi) do { lo = (f32x4){bflo((w)[0]), bfhi((w)[0]), bflo((w)[1]), bfhi((w)[1])}; hi = (f32x4){bflo((w)[2]), bfhi((w)[2]), bflo((w)[3]), bfhi((w)[3])}; } while (0)
; template <bool XINB, bool XOUTB> __device__ __forceinline__ void ph_rows(Frame& F, int nrows, const void* xin_l, const void* xin_c, void* xout_l, void* xout_c, const bf16* Y, const bf16* Ypart, ...
;     ...
;             if (!lat && Ypart) {
; #pragma unroll
;                 for (int jj = 0; jj < 4; ++jj) { f32x4 a0 = {0.f, 0.f, 0.f, 0.f}, a1 = a0;
; #pragma unroll
;                     for (int sp = 0; sp < KSPLIT; ++sp) { const v4u yw = *(const v4u*)(Ypart + ((size_t)sp * MC + (row - ML)) * D + ROWS_COL(jj)); f32x4 p0, p1; ROWS_UNPK(yw, p0, p1); a0 += p0; a1 += p1; }
;                     y[2 * jj] = a0; y[2 * jj + 1] = a1; }
	v_mov_b32_e32 v44, v176
	v_mov_b32_e32 v45, v177
	v_mov_b32_e32 v46, v178
	v_mov_b32_e32 v47, v179
	v_lshlrev_b32_e32 v54, 16, v44
	v_and_b32_e32 v55, 0xffff0000, v44
	v_lshlrev_b32_e32 v44, 16, v45
	v_and_b32_e32 v45, 0xffff0000, v45
	v_lshlrev_b32_e32 v58, 16, v46
	v_and_b32_e32 v59, 0xffff0000, v46
	v_lshlrev_b32_e32 v68, 16, v47
	v_and_b32_e32 v69, 0xffff0000, v47
	v_pk_add_f32 v[46:47], v[52:53], v[44:45]
	v_pk_add_f32 v[44:45], v[48:49], v[54:55]
	v_pk_add_f32 v[48:49], v[56:57], v[58:59]
	v_pk_add_f32 v[50:51], v[50:51], v[68:69]
	s_waitcnt vmcnt(7)
	v_mov_b32_e32 v52, v180
	v_mov_b32_e32 v53, v181
	v_mov_b32_e32 v54, v182
	v_mov_b32_e32 v55, v183
	v_lshlrev_b32_e32 v56, 16, v52
	v_and_b32_e32 v57, 0xffff0000, v52
	v_lshlrev_b32_e32 v52, 16, v53
	v_and_b32_e32 v53, 0xffff0000, v53
	v_lshlrev_b32_e32 v58, 16, v54
	v_and_b32_e32 v59, 0xffff0000, v54
	v_lshlrev_b32_e32 v54, 16, v55
	v_and_b32_e32 v55, 0xffff0000, v55
	v_pk_add_f32 v[68:69], v[52:53], 0 op_sel_hi:[1,0]
	v_pk_add_f32 v[70:71], v[54:55], 0 op_sel_hi:[1,0]
	v_pk_add_f32 v[56:57], v[56:57], 0 op_sel_hi:[1,0]
	v_pk_add_f32 v[58:59], v[58:59], 0 op_sel_hi:[1,0]
	s_waitcnt vmcnt(6)
	v_mov_b32_e32 v52, v184
	v_mov_b32_e32 v53, v185
	v_mov_b32_e32 v54, v186
	v_mov_b32_e32 v55, v187
	v_lshlrev_b32_e32 v72, 16, v52
	v_and_b32_e32 v73, 0xffff0000, v52
	v_lshlrev_b32_e32 v52, 16, v53
	v_and_b32_e32 v53, 0xffff0000, v53
	v_lshlrev_b32_e32 v74, 16, v54
	v_and_b32_e32 v75, 0xffff0000, v54
	v_lshlrev_b32_e32 v54, 16, v55
	v_and_b32_e32 v55, 0xffff0000, v55
	v_pk_add_f32 v[68:69], v[68:69], v[52:53]
	v_pk_add_f32 v[70:71], v[70:71], v[54:55]
	v_pk_add_f32 v[56:57], v[56:57], v[72:73]
	v_pk_add_f32 v[58:59], v[58:59], v[74:75]
	s_waitcnt vmcnt(5)
	v_mov_b32_e32 v52, v188
	v_mov_b32_e32 v53, v189
	v_mov_b32_e32 v54, v190
	v_mov_b32_e32 v55, v191
	v_lshlrev_b32_e32 v72, 16, v52
	v_and_b32_e32 v73, 0xffff0000, v52
	v_lshlrev_b32_e32 v52, 16, v53
	v_and_b32_e32 v53, 0xffff0000, v53
	v_lshlrev_b32_e32 v74, 16, v54
	v_and_b32_e32 v75, 0xffff0000, v54
	v_lshlrev_b32_e32 v54, 16, v55
	v_and_b32_e32 v55, 0xffff0000, v55
	v_pk_add_f32 v[56:57], v[56:57], v[72:73]
	v_pk_add_f32 v[68:69], v[68:69], v[52:53]
	v_pk_add_f32 v[72:73], v[58:59], v[74:75]
	v_pk_add_f32 v[58:59], v[70:71], v[54:55]
	s_waitcnt vmcnt(4)
	v_mov_b32_e32 v52, v192
	v_mov_b32_e32 v53, v193
	v_mov_b32_e32 v54, v194
	v_mov_b32_e32 v55, v195
	v_lshlrev_b32_e32 v70, 16, v52
	v_and_b32_e32 v71, 0xffff0000, v52
	v_lshlrev_b32_e32 v52, 16, v53
	v_and_b32_e32 v53, 0xffff0000, v53
	v_lshlrev_b32_e32 v74, 16, v54
	v_and_b32_e32 v75, 0xffff0000, v54
	v_lshlrev_b32_e32 v76, 16, v55
	v_and_b32_e32 v77, 0xffff0000, v55
	v_pk_add_f32 v[54:55], v[68:69], v[52:53]
	v_pk_add_f32 v[52:53], v[56:57], v[70:71]
	v_pk_add_f32 v[56:57], v[72:73], v[74:75]
	v_pk_add_f32 v[58:59], v[58:59], v[76:77]
	s_waitcnt vmcnt(3)
	v_mov_b32_e32 v66, v196
	v_mov_b32_e32 v67, v197
	v_mov_b32_e32 v68, v198
	v_mov_b32_e32 v69, v199
	v_lshlrev_b32_e32 v70, 16, v66
	v_and_b32_e32 v71, 0xffff0000, v66
	v_lshlrev_b32_e32 v66, 16, v67
	v_and_b32_e32 v67, 0xffff0000, v67
	v_pk_add_f32 v[74:75], v[66:67], 0 op_sel_hi:[1,0]
	v_lshlrev_b32_e32 v72, 16, v68
	v_and_b32_e32 v73, 0xffff0000, v68
	v_lshlrev_b32_e32 v68, 16, v69
	v_and_b32_e32 v69, 0xffff0000, v69
	v_pk_add_f32 v[70:71], v[70:71], 0 op_sel_hi:[1,0]
	v_pk_add_f32 v[68:69], v[68:69], 0 op_sel_hi:[1,0]
	v_pk_add_f32 v[72:73], v[72:73], 0 op_sel_hi:[1,0]
	s_waitcnt vmcnt(2)
	v_mov_b32_e32 v64, v200
	v_mov_b32_e32 v65, v201
	v_mov_b32_e32 v66, v202
	v_mov_b32_e32 v67, v203
	v_lshlrev_b32_e32 v76, 16, v64
	v_and_b32_e32 v77, 0xffff0000, v64
	v_lshlrev_b32_e32 v64, 16, v65
	v_and_b32_e32 v65, 0xffff0000, v65
	v_pk_add_f32 v[74:75], v[74:75], v[64:65]
	v_lshlrev_b32_e32 v78, 16, v66
	v_and_b32_e32 v79, 0xffff0000, v66
	v_lshlrev_b32_e32 v66, 16, v67
	v_and_b32_e32 v67, 0xffff0000, v67
	v_pk_add_f32 v[70:71], v[70:71], v[76:77]
	v_pk_add_f32 v[66:67], v[68:69], v[66:67]
	v_pk_add_f32 v[72:73], v[72:73], v[78:79]
	s_waitcnt vmcnt(1)
	v_mov_b32_e32 v62, v204
	v_mov_b32_e32 v63, v205
	v_mov_b32_e32 v64, v206
	v_mov_b32_e32 v65, v207
	v_lshlrev_b32_e32 v68, 16, v62
	v_and_b32_e32 v69, 0xffff0000, v62
	v_lshlrev_b32_e32 v62, 16, v63
	v_and_b32_e32 v63, 0xffff0000, v63
	v_pk_add_f32 v[68:69], v[70:71], v[68:69]
	v_pk_add_f32 v[70:71], v[74:75], v[62:63]
	v_lshlrev_b32_e32 v76, 16, v64
	v_and_b32_e32 v77, 0xffff0000, v64
	v_lshlrev_b32_e32 v78, 16, v65
	v_and_b32_e32 v79, 0xffff0000, v65
	v_pk_add_f32 v[64:65], v[72:73], v[76:77]
	v_pk_add_f32 v[66:67], v[66:67], v[78:79]
	s_waitcnt vmcnt(0)
	v_mov_b32_e32 v60, v208
	v_mov_b32_e32 v61, v209
	v_mov_b32_e32 v62, v210
	v_mov_b32_e32 v63, v211
	v_lshlrev_b32_e32 v72, 16, v60
	v_and_b32_e32 v73, 0xffff0000, v60
	v_lshlrev_b32_e32 v60, 16, v61
	v_and_b32_e32 v61, 0xffff0000, v61
	v_lshlrev_b32_e32 v74, 16, v62
	v_and_b32_e32 v75, 0xffff0000, v62
	v_lshlrev_b32_e32 v76, 16, v63
	v_and_b32_e32 v77, 0xffff0000, v63
	v_pk_add_f32 v[62:63], v[70:71], v[60:61]
	v_pk_add_f32 v[60:61], v[68:69], v[72:73]
	v_pk_add_f32 v[66:67], v[66:67], v[76:77]
	v_pk_add_f32 v[64:65], v[64:65], v[74:75]
